# A2 pass: a workgroup pair handles residue classes congruent mod 4 (rho, rho+4, rho+8, rho+12) so the dilation-4 tiles share cache lines
# speedup vs baseline: 1.0076x; 1.0030x over previous
; #define LAS __attribute__((address_space(3)))
; DI float ex2(float x) { return __builtin_amdgcn_exp2f(x); }
; DI float a_bound(const bf16x8 (&qf)[2], const float* kmax_l, int b, int h) { return sqrtf(q_norm2(qf) * (kmax_l[b * 128 + 8 + 2 * h] + kmax_l[b * 128 + 9 + 2 * h])) * 1.01f + 0.05f; }
; #define A_LOAD(R, t_) do { int tb_, sd_, md_; a_desc((t_), a0, rho, tb_, sd_, md_); tile_load(R, kb, vb, tb_, sd_, lane); } while (0)
; DI float q_norm2(const bf16x8 (&qf)[2]) { float a = sumsq8(qf[0]) + sumsq8(qf[1]); a += __shfl_xor(a, 16); a += __shfl_xor(a, 32); return a; }
; DI void a_desc(int ti, int a0, int rho, int& tokbase, int& stride, int& maxd) {
; DI void mixerA2_unit(int u, const bf16* PROJ, bf16* YC, const float* LPA, const float* kmax_l, LAS char* vt, int wave, int lane) {
;     const int b = u >> 6, h = (u >> 4) & 3, rho = u & 15, a0 = 16 * wave, r = lane & 15, g = lane >> 4;
;     const bf16* kb = slab(PROJ, C_AK + h * 64, b); const bf16* vb = slab(PROJ, C_AV + h * 64, b);
;     const int tq = 16 * (a0 + r) + rho;
;     bf16x8 qf[2];
; #pragma unroll
;     for (int ks = 0; ks < 2; ++ks) qf[ks] = *(const bf16x8*)(slab(PROJ, C_AQ + h * 64, b) + (size_t)tq * 64 + 32 * ks + 8 * g);
;     const float nslope2 = -ex2(-(float)(2 * h + 1)) * LOG2E;
;     const float bound = a_bound(qf, kmax_l, b, h);
;     const f32x4 cinit = {-bound, -bound, -bound, -bound};
;     f32x4 o[4], ol = {0.f, 0.f, 0.f, 0.f};
; #pragma unroll
;     for (int c = 0; c < 4; ++c) o[c] = ol;
;     TileRegs R0, R1, R2;
;     ...
;     A_LOAD(R0, 0); A_LOAD(R1, 1); A_LOAD(R2, 2);
.Lsw_a2:
	v_readlane_b32 s0, v253, 0
	v_mbcnt_lo_u32_b32 v4, -1, 0
	v_mbcnt_hi_u32_b32 v4, -1, v4
	s_waitcnt lgkmcnt(0)
	s_nop 0
	v_add_u32_e32 v5, s0, v4
	v_readlane_b32 s0, v254, 31
	v_readlane_b32 s1, v254, 32
	s_andn2_b64 vcc, exec, s[0:1]
	v_readfirstlane_b32 s0, v5
	s_cbranch_vccnz .LBB0_423
	v_writelane_b32 v255, s26, 35
	s_ashr_i32 s2, s0, 6
	s_lshl_b32 s0, s2, 14
	v_writelane_b32 v255, s27, 36
	s_add_i32 s4, s0, 0
	v_readlane_b32 s0, v255, 27
	v_readlane_b32 s1, v255, 28
	s_lshl_b32 s34, s0, 10
	s_lshl_b64 s[0:1], s[34:35], 2
	v_readlane_b32 s20, v253, 42
	v_readlane_b32 s21, v253, 43
	s_add_u32 s60, s20, s0
	s_addc_u32 s61, s21, s1
	v_and_b32_e32 v7, 15, v4
	v_bfe_u32 v8, v4, 4, 2
	s_lshl_b32 s62, s2, 8
	v_lshl_or_b32 v149, v7, 4, s62
	v_lshlrev_b32_e32 v167, 6, v8
	v_lshlrev_b32_e32 v148, 3, v8
	v_sub_u32_e32 v8, v167, v149
	v_mov_b32_e32 v14, s4
	s_movk_i32 s0, 0x90
	v_mad_u32_u24 v169, v7, s0, v14
	v_add_u32_e32 v7, 0x400, v8
	v_cmp_gt_u32_e64 s[36:37], s14, v7
	v_add_u32_e32 v7, 16, v8
	v_cvt_f32_i32_e32 v171, v7
	v_add_u32_e32 v7, 32, v8
	v_and_b32_e32 v9, 64, v224
	v_add_u32_e32 v15, 0x410, v8
	v_cvt_f32_i32_e32 v172, v7
	v_add_u32_e32 v7, 48, v8
	s_add_i32 s63, s62, 0xffffff00
	s_add_i32 s64, s62, 0xffffff80
	v_xor_b32_e32 v6, 16, v224
	v_add_u32_e32 v9, 64, v9
	v_cmp_gt_u32_e64 s[38:39], s14, v15
	v_add_u32_e32 v15, 0x420, v8
	v_cvt_f32_i32_e32 v173, v7
	v_add_u32_e32 v7, 0x100, v8
	s_cmpk_lt_u32 s63, 0x800
	v_cmp_lt_i32_e32 vcc, v6, v9
	v_cmp_gt_u32_e64 s[40:41], s14, v15
	v_add_u32_e32 v15, 0x430, v8
	v_cvt_f32_i32_e32 v174, v7
	v_add_u32_e32 v7, 0x110, v8
	s_cselect_b64 s[54:55], -1, 0
	s_cmpk_lt_u32 s64, 0x800
	v_cndmask_b32_e32 v6, v224, v6, vcc
	v_cmp_gt_u32_e64 s[42:43], s14, v15
	v_add_u32_e32 v15, 0x500, v8
	v_cvt_f32_i32_e32 v175, v7
	v_add_u32_e32 v7, 0x120, v8
	s_cselect_b64 s[90:91], -1, 0
	s_add_i32 s65, s62, 0x100
	v_lshlrev_b32_e32 v160, 2, v6
	v_xor_b32_e32 v6, 32, v224
	v_cmp_gt_u32_e64 s[44:45], s14, v15
	v_add_u32_e32 v15, 0x510, v8
	v_cvt_f32_i32_e32 v176, v7
	v_add_u32_e32 v7, 0x130, v8
	s_cmpk_lt_u32 s62, 0x800
	v_and_b32_e32 v5, 63, v4
	v_cmp_lt_i32_e32 vcc, v6, v9
	v_bfe_u32 v9, v4, 3, 3
	v_lshlrev_b32_e32 v13, 4, v4
	v_cvt_f32_i32_e32 v170, v8
	v_cmp_gt_u32_e64 s[46:47], s14, v15
	v_add_u32_e32 v15, 0x520, v8
	v_add_u32_e32 v8, 0x530, v8
	v_cvt_f32_i32_e32 v177, v7
	s_cselect_b64 s[20:21], -1, 0
	s_add_i32 s68, s62, 0x180
	v_cndmask_b32_e32 v6, v224, v6, vcc
	v_lshlrev_b32_e32 v5, 3, v5
	v_or_b32_e32 v10, 8, v9
	v_and_b32_e32 v13, 0x70, v13
	v_cmp_gt_u32_e64 s[50:51], s14, v8
	v_bfe_u32 v7, v4, 2, 4
	s_cmpk_lt_u32 s65, 0x800
	v_and_b32_e32 v8, 7, v4
	v_lshlrev_b32_e32 v161, 2, v6
	v_and_b32_e32 v6, 56, v5
	v_or_b32_e32 v11, 16, v9
	v_or_b32_e32 v12, 24, v9
	v_add_u32_e32 v13, s4, v13
	v_mul_u32_u24_e32 v166, 0x90, v9
	v_and_b32_e32 v168, 48, v4
	v_mad_u32_u24 v7, v7, s0, v14
	v_and_b32_e32 v5, 24, v5
	s_mov_b64 s[56:57], s[96:97]
	s_cselect_b64 s[96:97], -1, 0
	s_cmpk_lt_u32 s68, 0x800
	v_lshlrev_b32_e32 v4, 3, v8
	v_lshl_add_u32 v182, v8, 4, s4
	v_mul_u32_u24_e32 v8, 0x90, v10
	v_lshlrev_b32_e32 v162, 4, v9
	v_lshlrev_b32_e32 v163, 4, v10
	v_lshlrev_b32_e32 v164, 4, v11
	v_lshlrev_b32_e32 v165, 4, v12
	v_cmp_gt_u32_e64 s[48:49], s14, v15
	v_lshlrev_b32_e32 v178, 2, v9
	v_lshlrev_b32_e32 v179, 2, v10
	v_lshlrev_b32_e32 v180, 2, v11
	v_lshlrev_b32_e32 v181, 2, v12
	s_cselect_b64 s[26:27], -1, 0
	v_lshlrev_b32_e32 v150, 1, v6
	v_add_u32_e32 v183, v13, v166
	v_add_u32_e32 v184, v7, v5
	v_lshlrev_b32_e32 v152, 1, v4
	v_add_u32_e32 v185, v182, v8
	v_readlane_b32 s69, v255, 40
	s_and_b32 s98, s69, 1
	s_lshl_b32 s98, s98, 3
	s_bfe_u32 s99, s69, 0x20001
	s_or_b32 s98, s98, s99
	s_andn2_b32 s69, s69, 7
	s_lshl_b32 s69, s69, 1
	s_or_b32 s69, s69, s98
	s_movk_i32 s58, 0x7bc
	s_movk_i32 s67, 0x7fc
	s_movk_i32 s59, 0x7b8
	s_movk_i32 s52, 0x7b4
.LBB0_421:
	s_ashr_i32 s94, s69, 6
	s_bfe_u32 s2, s69, 0x20004
	s_and_b32 s5, s69, 15
	s_ashr_i32 s95, s94, 31
	s_lshl_b32 s0, s2, 21
	s_add_u32 s4, s10, s0
	s_addc_u32 s16, s11, 0
	s_lshl_b64 s[0:1], s[94:95], 18
	v_or_b32_e32 v154, s5, v149
	s_add_u32 s30, s4, s0
	v_ashrrev_i32_e32 v155, 31, v154
	s_addc_u32 s31, s16, s1
	v_lshlrev_b64 v[4:5], 7, v[154:155]
	v_lshl_add_u64 v[4:5], s[30:31], 0, v[4:5]
	v_lshlrev_b32_e32 v188, 1, v148
	v_lshl_add_u64 v[4:5], v[4:5], 0, v[188:189]
	global_load_dwordx4 v[8:11], v[4:5], off
	s_nop 0
	global_load_dwordx4 v[4:7], v[4:5], off offset:64
	s_lshl_b32 s0, s2, 1
	s_or_b32 s1, s0, 1
	v_cvt_f32_ubyte0_e32 v12, s1
	v_exp_f32_e64 v18, -v12
	s_lshl_b32 s1, s94, 7
	s_or_b32 s0, s0, s1
	s_ashr_i32 s1, s0, 31
	s_lshl_b64 s[0:1], s[0:1], 2
	s_add_u32 s0, s60, s0
	s_addc_u32 s1, s61, s1
	v_mov_b32_e32 v151, v189
	v_mul_f32_e32 v153, 0xbfb8aa3b, v18
	s_or_b32 s4, s5, 0x600
	s_or_b32 s33, s5, s64
	s_lshl_b32 s34, s2, 2
	s_waitcnt vmcnt(0)
	v_and_b32_e32 v14, 0xffff0000, v8
	v_and_b32_e32 v15, 0xffff0000, v4
	v_lshlrev_b32_e32 v13, 16, v4
	v_lshlrev_b32_e32 v12, 16, v8
	v_pk_mul_f32 v[14:15], v[14:15], v[14:15]
	v_and_b32_e32 v17, 0xffff0000, v5
	v_and_b32_e32 v16, 0xffff0000, v9
	v_pk_fma_f32 v[12:13], v[12:13], v[12:13], v[14:15]
	v_lshlrev_b32_e32 v15, 16, v5
	v_lshlrev_b32_e32 v14, 16, v9
	v_pk_mul_f32 v[16:17], v[16:17], v[16:17]
	s_nop 0
	v_pk_fma_f32 v[14:15], v[14:15], v[14:15], v[16:17]
	v_and_b32_e32 v17, 0xffff0000, v6
	v_and_b32_e32 v16, 0xffff0000, v10
	v_pk_add_f32 v[12:13], v[12:13], v[14:15]
	v_lshlrev_b32_e32 v15, 16, v6
	v_lshlrev_b32_e32 v14, 16, v10
	v_pk_mul_f32 v[16:17], v[16:17], v[16:17]
	s_nop 0
	v_pk_fma_f32 v[14:15], v[14:15], v[14:15], v[16:17]
	v_and_b32_e32 v17, 0xffff0000, v7
	v_and_b32_e32 v16, 0xffff0000, v11
	v_pk_add_f32 v[12:13], v[14:15], v[12:13]
	v_lshlrev_b32_e32 v15, 16, v7
	v_lshlrev_b32_e32 v14, 16, v11
	v_pk_mul_f32 v[16:17], v[16:17], v[16:17]
	s_nop 0
	v_pk_fma_f32 v[14:15], v[14:15], v[14:15], v[16:17]
	global_load_dwordx2 v[16:17], v189, s[0:1] offset:32
	v_pk_add_f32 v[12:13], v[14:15], v[12:13]
	s_waitcnt vmcnt(0)
; DI float ex2(float x) { return __builtin_amdgcn_exp2f(x); }
; DI float a_bound(const bf16x8 (&qf)[2], const float* kmax_l, int b, int h) { return sqrtf(q_norm2(qf) * (kmax_l[b * 128 + 8 + 2 * h] + kmax_l[b * 128 + 9 + 2 * h])) * 1.01f + 0.05f; }
; #define A_LOAD(R, t_) do { int tb_, sd_, md_; a_desc((t_), a0, rho, tb_, sd_, md_); tile_load(R, kb, vb, tb_, sd_, lane); } while (0)
; #define A_STAGE(S, R, t_) do { int tb_, sd_, md_; a_desc((t_), a0, rho, tb_, sd_, md_); a_stage(S, R, vt, (t_) & 1, qf, cinit, tb_, sd_, md_, tq, nslope2, lane); } while (0)
; DI void tile_load(TileRegs& R, const bf16* kb, const bf16* vb, int tokbase, int stride, int lane) {
; #pragma unroll
;     for (int it = 0; it < 4; ++it) { const int n = lane + 64 * it, row = n >> 3, ch = n & 7; int tok = tokbase + stride * row; tok = min(max(tok, 0), T - 1);
;         R.k[it] = *(const u32x4*)(kb + (size_t)tok * 64 + ch * 8); R.v[it] = *(const u32x4*)(vb + (size_t)tok * 64 + ch * 8); }
; }
; DI void mixerA2_unit(int u, const bf16* PROJ, bf16* YC, const float* LPA, const float* kmax_l, LAS char* vt, int wave, int lane) {
;     ...
;     const float nslope2 = -ex2(-(float)(2 * h + 1)) * LOG2E;
;     const float bound = a_bound(qf, kmax_l, b, h);
;     const f32x4 cinit = {-bound, -bound, -bound, -bound};
;     f32x4 o[4], ol = {0.f, 0.f, 0.f, 0.f};
; #pragma unroll
;     for (int c = 0; c < 4; ++c) o[c] = ol;
;     TileRegs R0, R1, R2;
;     ...
;     A_LOAD(R0, 0); A_LOAD(R1, 1); A_LOAD(R2, 2);
;     f32x4 sA[2], sB[2];
;     ...
;     A_STAGE(sA, R0, 0); A_LOAD(R0, 3);
	v_mov_b32_e32 v14, v17
	v_add_f32_e32 v12, v12, v13
	ds_bpermute_b32 v13, v160, v12
	s_waitcnt lgkmcnt(0)
	v_add_f32_e32 v13, v12, v13
	ds_bpermute_b32 v15, v161, v13
	v_mov_b32_e32 v12, v16
	v_lshl_add_u64 v[16:17], s[30:31], 0, v[150:151]
	v_add_u32_e32 v151, v169, v168
	s_waitcnt lgkmcnt(0)
	v_pk_add_f32 v[12:13], v[12:13], v[14:15]
	s_nop 0
	v_mul_f32_e32 v12, v12, v13
	v_cmp_gt_f32_e32 vcc, s92, v12
	v_mul_f32_e32 v13, 0x4f800000, v12
	s_nop 0
	v_cndmask_b32_e32 v12, v12, v13, vcc
	v_sqrt_f32_e32 v13, v12
	s_nop 0
	v_add_u32_e32 v14, -1, v13
	v_fma_f32 v15, -v14, v13, v12
	v_cmp_ge_f32_e64 s[0:1], 0, v15
	v_add_u32_e32 v15, 1, v13
	s_nop 0
	v_cndmask_b32_e64 v14, v13, v14, s[0:1]
	v_fma_f32 v13, -v15, v13, v12
	v_cmp_lt_f32_e64 s[0:1], 0, v13
	s_nop 1
	v_cndmask_b32_e64 v13, v14, v15, s[0:1]
	s_mov_b64 s[0:1], 0x800000
	v_lshl_add_u64 v[156:157], v[16:17], 0, s[0:1]
	s_mov_b64 s[0:1], 0x1000000
	v_lshl_add_u64 v[158:159], v[16:17], 0, s[0:1]
	v_or_b32_e32 v16, s5, v162
	v_lshlrev_b32_e32 v188, 7, v16
	v_lshl_add_u64 v[16:17], v[156:157], 0, v[188:189]
	global_load_dwordx4 v[52:55], v[16:17], off
	v_lshl_add_u64 v[16:17], v[158:159], 0, v[188:189]
	global_load_dwordx4 v[56:59], v[16:17], off
	v_or_b32_e32 v16, s5, v163
	v_lshlrev_b32_e32 v188, 7, v16
	v_lshl_add_u64 v[16:17], v[156:157], 0, v[188:189]
	global_load_dwordx4 v[60:63], v[16:17], off
	v_lshl_add_u64 v[16:17], v[158:159], 0, v[188:189]
	global_load_dwordx4 v[64:67], v[16:17], off
	v_or_b32_e32 v16, s5, v164
	v_lshlrev_b32_e32 v188, 7, v16
	v_lshl_add_u64 v[16:17], v[156:157], 0, v[188:189]
	global_load_dwordx4 v[68:71], v[16:17], off
	v_lshl_add_u64 v[16:17], v[158:159], 0, v[188:189]
	global_load_dwordx4 v[72:75], v[16:17], off
	v_or_b32_e32 v16, s5, v165
	v_lshlrev_b32_e32 v188, 7, v16
	v_lshl_add_u64 v[16:17], v[156:157], 0, v[188:189]
	global_load_dwordx4 v[76:79], v[16:17], off
	v_lshl_add_u64 v[16:17], v[158:159], 0, v[188:189]
	global_load_dwordx4 v[80:83], v[16:17], off
	s_or_b32 s0, s5, 0x200
	v_or_b32_e32 v16, s0, v162
	v_lshlrev_b32_e32 v188, 7, v16
	v_lshl_add_u64 v[16:17], v[156:157], 0, v[188:189]
	v_lshl_add_u64 v[20:21], v[158:159], 0, v[188:189]
	global_load_dwordx4 v[16:19], v[16:17], off
	s_or_b32 s1, s5, 0x400
	global_load_dwordx4 v[84:87], v[20:21], off
	v_or_b32_e32 v20, s0, v163
	v_lshlrev_b32_e32 v188, 7, v20
	v_lshl_add_u64 v[20:21], v[156:157], 0, v[188:189]
	global_load_dwordx4 v[88:91], v[20:21], off
	v_lshl_add_u64 v[20:21], v[158:159], 0, v[188:189]
	global_load_dwordx4 v[92:95], v[20:21], off
	v_or_b32_e32 v20, s0, v164
	v_lshlrev_b32_e32 v188, 7, v20
	v_lshl_add_u64 v[20:21], v[156:157], 0, v[188:189]
	global_load_dwordx4 v[96:99], v[20:21], off
	v_lshl_add_u64 v[20:21], v[158:159], 0, v[188:189]
	global_load_dwordx4 v[100:103], v[20:21], off
	v_or_b32_e32 v20, s0, v165
	v_lshlrev_b32_e32 v188, 7, v20
	v_lshl_add_u64 v[20:21], v[156:157], 0, v[188:189]
	global_load_dwordx4 v[104:107], v[20:21], off
	v_lshl_add_u64 v[20:21], v[158:159], 0, v[188:189]
	global_load_dwordx4 v[108:111], v[20:21], off
	v_or_b32_e32 v20, s1, v162
	v_lshlrev_b32_e32 v188, 7, v20
	v_or_b32_e32 v28, s1, v163
	v_lshl_add_u64 v[20:21], v[156:157], 0, v[188:189]
	v_lshl_add_u64 v[24:25], v[158:159], 0, v[188:189]
	v_lshlrev_b32_e32 v188, 7, v28
	v_or_b32_e32 v36, s1, v164
	v_lshl_add_u64 v[28:29], v[156:157], 0, v[188:189]
	v_lshl_add_u64 v[32:33], v[158:159], 0, v[188:189]
	v_lshlrev_b32_e32 v188, 7, v36
	v_or_b32_e32 v44, s1, v165
	v_lshl_add_u64 v[36:37], v[156:157], 0, v[188:189]
	v_lshl_add_u64 v[40:41], v[158:159], 0, v[188:189]
	v_lshlrev_b32_e32 v188, 7, v44
	v_lshl_add_u64 v[44:45], v[156:157], 0, v[188:189]
	v_lshl_add_u64 v[48:49], v[158:159], 0, v[188:189]
	global_load_dwordx4 v[20:23], v[20:21], off
	v_mul_f32_e32 v14, 0x37800000, v13
	global_load_dwordx4 v[24:27], v[24:25], off
	v_cndmask_b32_e32 v13, v13, v14, vcc
	global_load_dwordx4 v[28:31], v[28:29], off
	v_cmp_class_f32_e32 vcc, v12, v226
	global_load_dwordx4 v[32:35], v[32:33], off
	s_nop 0
	global_load_dwordx4 v[36:39], v[36:37], off
	v_cndmask_b32_e32 v12, v13, v12, vcc
	global_load_dwordx4 v[40:43], v[40:41], off
	v_fmamk_f32 v12, v12, 0x3f8147ae, v227
	global_load_dwordx4 v[44:47], v[44:45], off
	v_xor_b32_e32 v12, 0x80000000, v12
	global_load_dwordx4 v[48:51], v[48:49], off
	s_waitcnt vmcnt(22)
	ds_write_b128 v183, v[56:59]
	ds_write_b128 v183, v[52:55] offset:9216
	s_waitcnt vmcnt(20)
	ds_write_b128 v183, v[64:67] offset:1152
	ds_write_b128 v183, v[60:63] offset:10368
	s_waitcnt vmcnt(18)
	ds_write_b128 v183, v[72:75] offset:2304
	ds_write_b128 v183, v[68:71] offset:11520
	s_waitcnt vmcnt(16)
	ds_write_b128 v183, v[80:83] offset:3456
	ds_write_b128 v183, v[76:79] offset:12672
	ds_read_b128 v[52:55], v151 offset:9216
	ds_read_b128 v[56:59], v151 offset:9280
	v_mov_b32_e32 v13, v12
	v_mov_b32_e32 v14, v12
	v_mov_b32_e32 v15, v12
	v_or_b32_e32 v60, s4, v163
	v_or_b32_e32 v68, s4, v164
	s_waitcnt lgkmcnt(1)
	v_mfma_f32_16x16x32_bf16 v[52:55], v[52:55], v[8:11], v[12:15]
	v_or_b32_e32 v76, s4, v165
	s_waitcnt lgkmcnt(0)
	v_mfma_f32_16x16x32_bf16 v[52:55], v[56:59], v[4:7], v[52:55]
	ds_read_b128 v[56:59], v151 offset:11584
	s_nop 6
	v_fma_f32 v52, |v170|, v153, v52
	v_cndmask_b32_e64 v116, v234, v52, s[36:37]
	v_fma_f32 v52, |v171|, v153, v53
	v_cndmask_b32_e64 v117, v234, v52, s[38:39]
	v_fma_f32 v52, |v172|, v153, v54
	v_cndmask_b32_e64 v118, v234, v52, s[40:41]
	v_fma_f32 v52, |v173|, v153, v55
	v_cndmask_b32_e64 v119, v234, v52, s[42:43]
	ds_read_b128 v[52:55], v151 offset:11520
	s_waitcnt lgkmcnt(0)
; #define A_LOAD(R, t_) do { int tb_, sd_, md_; a_desc((t_), a0, rho, tb_, sd_, md_); tile_load(R, kb, vb, tb_, sd_, lane); } while (0)
; #define A_STAGE(S, R, t_) do { int tb_, sd_, md_; a_desc((t_), a0, rho, tb_, sd_, md_); a_stage(S, R, vt, (t_) & 1, qf, cinit, tb_, sd_, md_, tq, nslope2, lane); } while (0)
; DI void mixerA2_unit(int u, const bf16* PROJ, bf16* YC, const float* LPA, const float* kmax_l, LAS char* vt, int wave, int lane) {
;     ...
;     A_LOAD(R0, 0); A_LOAD(R1, 1); A_LOAD(R2, 2);
;     f32x4 sA[2], sB[2];
;     ...
;     A_STAGE(sA, R0, 0); A_LOAD(R0, 3);
;     A_STAGE(sB, R1, 1); A_LOAD(R1, 4);
;     fb_update(o, ol, sA[0], sA[1], vt, lane);
;     A_STAGE(sA, R2, 2); A_LOAD(R2, 5);
;     fb_update(o, ol, sB[0], sB[1], vt + A_V1, lane);
;     A_STAGE(sB, R0, 3); A_LOAD(R0, 6);
	v_mfma_f32_16x16x32_bf16 v[52:55], v[52:55], v[8:11], v[12:15]
	v_mfma_f32_16x16x32_bf16 v[52:55], v[56:59], v[4:7], v[52:55]
	s_nop 7
	v_fma_f32 v52, |v174|, v153, v52
	v_cndmask_b32_e64 v120, v234, v52, s[44:45]
	v_fma_f32 v52, |v175|, v153, v53
	v_cndmask_b32_e64 v121, v234, v52, s[46:47]
	v_fma_f32 v52, |v176|, v153, v54
	v_cndmask_b32_e64 v122, v234, v52, s[48:49]
	v_fma_f32 v52, |v177|, v153, v55
	v_cndmask_b32_e64 v123, v234, v52, s[50:51]
	v_or_b32_e32 v52, s4, v162
	v_lshlrev_b32_e32 v188, 7, v52
	v_lshl_add_u64 v[52:53], v[156:157], 0, v[188:189]
	v_lshl_add_u64 v[56:57], v[158:159], 0, v[188:189]
	v_lshlrev_b32_e32 v188, 7, v60
	v_lshl_add_u64 v[60:61], v[156:157], 0, v[188:189]
	v_lshl_add_u64 v[64:65], v[158:159], 0, v[188:189]
	v_lshlrev_b32_e32 v188, 7, v68
	v_lshl_add_u64 v[68:69], v[156:157], 0, v[188:189]
	v_lshl_add_u64 v[72:73], v[158:159], 0, v[188:189]
	v_lshlrev_b32_e32 v188, 7, v76
	v_lshl_add_u64 v[76:77], v[156:157], 0, v[188:189]
	v_lshl_add_u64 v[80:81], v[158:159], 0, v[188:189]
	global_load_dwordx4 v[52:55], v[52:53], off
	s_nop 0
	global_load_dwordx4 v[56:59], v[56:57], off
	s_nop 0
	global_load_dwordx4 v[60:63], v[60:61], off
	s_nop 0
	global_load_dwordx4 v[64:67], v[64:65], off
	s_nop 0
	global_load_dwordx4 v[68:71], v[68:69], off
	s_nop 0
	global_load_dwordx4 v[72:75], v[72:73], off
	s_nop 0
	global_load_dwordx4 v[76:79], v[76:77], off
	s_nop 0
	global_load_dwordx4 v[80:83], v[80:81], off
	s_waitcnt vmcnt(22)
	ds_write_b128 v183, v[84:87] offset:4608
	ds_write_b128 v183, v[16:19] offset:9216
	s_waitcnt vmcnt(20)
	ds_write_b128 v183, v[92:95] offset:5760
	ds_write_b128 v183, v[88:91] offset:10368
	s_waitcnt vmcnt(18)
	ds_write_b128 v183, v[100:103] offset:6912
	ds_write_b128 v183, v[96:99] offset:11520
	s_waitcnt vmcnt(16)
	ds_write_b128 v183, v[108:111] offset:8064
	ds_write_b128 v183, v[104:107] offset:12672
	v_or_b32_e32 v16, s0, v167
	v_sub_u32_e32 v88, v16, v154
	ds_read_b128 v[16:19], v151 offset:9216
	ds_read_b128 v[84:87], v151 offset:9280
	s_waitcnt lgkmcnt(1)
	v_mfma_f32_16x16x32_bf16 v[16:19], v[16:19], v[8:11], v[12:15]
	s_or_b32 s0, s5, s63
	s_waitcnt lgkmcnt(0)
	v_mfma_f32_16x16x32_bf16 v[16:19], v[84:87], v[4:7], v[16:19]
	v_add_u32_e32 v84, 0x400, v88
	v_cmp_gt_u32_e32 vcc, s14, v84
	v_cvt_f32_i32_e32 v84, v88
	s_nop 4
	v_fma_f32 v16, |v84|, v153, v16
	v_cndmask_b32_e32 v128, v234, v16, vcc
	v_add_u32_e32 v16, 16, v88
	v_cvt_f32_i32_e32 v16, v16
	v_add_u32_e32 v84, 0x410, v88
	v_cmp_gt_u32_e32 vcc, s14, v84
	ds_read_b128 v[84:87], v151 offset:11584
	v_fma_f32 v16, |v16|, v153, v17
	v_cndmask_b32_e32 v129, v234, v16, vcc
	v_add_u32_e32 v16, 32, v88
	v_cvt_f32_i32_e32 v16, v16
	v_add_u32_e32 v17, 0x420, v88
	v_cmp_gt_u32_e32 vcc, s14, v17
	v_add_u32_e32 v17, 0x430, v88
	v_fma_f32 v16, |v16|, v153, v18
	v_cndmask_b32_e32 v130, v234, v16, vcc
	v_add_u32_e32 v16, 48, v88
	v_cvt_f32_i32_e32 v16, v16
	v_cmp_gt_u32_e32 vcc, s14, v17
	v_exp_f32_e32 v128, v128
	v_exp_f32_e32 v129, v129
	v_fma_f32 v16, |v16|, v153, v19
	v_cndmask_b32_e32 v131, v234, v16, vcc
	ds_read_b128 v[16:19], v151 offset:11520
	s_waitcnt lgkmcnt(0)
	v_mfma_f32_16x16x32_bf16 v[16:19], v[16:19], v[8:11], v[12:15]
	v_exp_f32_e32 v130, v130
	v_exp_f32_e32 v131, v131
	v_cvt_pk_bf16_f32 v198, v128, v129
	v_mfma_f32_16x16x32_bf16 v[16:19], v[84:87], v[4:7], v[16:19]
	v_add_u32_e32 v84, 0x100, v88
	v_cvt_f32_i32_e32 v84, v84
	v_add_u32_e32 v85, 0x500, v88
	v_cmp_gt_u32_e32 vcc, s14, v85
	v_cvt_pk_bf16_f32 v199, v130, v131
	s_nop 2
	v_fma_f32 v16, |v84|, v153, v16
	v_cndmask_b32_e32 v136, v234, v16, vcc
	v_add_u32_e32 v16, 0x110, v88
	v_cvt_f32_i32_e32 v16, v16
	v_add_u32_e32 v84, 0x510, v88
	v_cmp_gt_u32_e32 vcc, s14, v84
	v_exp_f32_e32 v136, v136
	v_fma_f32 v16, |v16|, v153, v17
	v_cndmask_b32_e32 v137, v234, v16, vcc
	v_add_u32_e32 v16, 0x120, v88
	v_cvt_f32_i32_e32 v16, v16
	v_add_u32_e32 v17, 0x520, v88
	v_cmp_gt_u32_e32 vcc, s14, v17
	v_add_u32_e32 v17, 0x530, v88
	v_fma_f32 v16, |v16|, v153, v18
	v_cndmask_b32_e32 v138, v234, v16, vcc
	v_add_u32_e32 v16, 0x130, v88
	v_cvt_f32_i32_e32 v16, v16
	v_cmp_gt_u32_e32 vcc, s14, v17
	v_exp_f32_e32 v18, v117
	v_exp_f32_e32 v117, v122
	v_fma_f32 v16, |v16|, v153, v19
	v_cndmask_b32_e32 v139, v234, v16, vcc
	v_add_u32_e32 v16, s0, v178
	v_med3_i32 v16, v16, 0, v233
	v_lshlrev_b32_e32 v188, 7, v16
	v_lshl_add_u64 v[16:17], v[156:157], 0, v[188:189]
	global_load_dwordx4 v[84:87], v[16:17], off
	v_lshl_add_u64 v[16:17], v[158:159], 0, v[188:189]
	global_load_dwordx4 v[88:91], v[16:17], off
	v_add_u32_e32 v16, s0, v179
	v_med3_i32 v16, v16, 0, v233
	v_lshlrev_b32_e32 v188, 7, v16
	v_lshl_add_u64 v[16:17], v[156:157], 0, v[188:189]
	global_load_dwordx4 v[92:95], v[16:17], off
	v_lshl_add_u64 v[16:17], v[158:159], 0, v[188:189]
	global_load_dwordx4 v[96:99], v[16:17], off
	v_add_u32_e32 v16, s0, v180
	v_med3_i32 v16, v16, 0, v233
	v_lshlrev_b32_e32 v188, 7, v16
	v_lshl_add_u64 v[16:17], v[156:157], 0, v[188:189]
	global_load_dwordx4 v[100:103], v[16:17], off
	v_lshl_add_u64 v[16:17], v[158:159], 0, v[188:189]
	global_load_dwordx4 v[104:107], v[16:17], off
	v_add_u32_e32 v16, s0, v181
	v_med3_i32 v16, v16, 0, v233
	v_lshlrev_b32_e32 v188, 7, v16
	v_lshl_add_u64 v[16:17], v[156:157], 0, v[188:189]
	global_load_dwordx4 v[108:111], v[16:17], off
	v_lshl_add_u64 v[16:17], v[158:159], 0, v[188:189]
	global_load_dwordx4 v[112:115], v[16:17], off
	v_exp_f32_e32 v16, v116
	v_exp_f32_e32 v17, v120
	v_exp_f32_e32 v19, v121
	v_exp_f32_e32 v116, v118
	v_exp_f32_e32 v118, v119
	v_exp_f32_e32 v119, v123
	ds_read_b64_tr_b16 v[122:123], v184 offset:2304
	ds_read_b64_tr_b16 v[120:121], v184
	ds_read_b64_tr_b16 v[124:125], v184 offset:32
	ds_read_b64_tr_b16 v[126:127], v184 offset:2336
	ds_read_b64_tr_b16 v[132:133], v184 offset:64
	ds_read_b64_tr_b16 v[134:135], v184 offset:2368
	ds_read_b64_tr_b16 v[144:145], v184 offset:96
	ds_read_b64_tr_b16 v[146:147], v184 offset:2400
	s_waitcnt vmcnt(22)
; #define A_LOAD(R, t_) do { int tb_, sd_, md_; a_desc((t_), a0, rho, tb_, sd_, md_); tile_load(R, kb, vb, tb_, sd_, lane); } while (0)
; #define A_STAGE(S, R, t_) do { int tb_, sd_, md_; a_desc((t_), a0, rho, tb_, sd_, md_); a_stage(S, R, vt, (t_) & 1, qf, cinit, tb_, sd_, md_, tq, nslope2, lane); } while (0)
; DI void mixerA2_unit(int u, const bf16* PROJ, bf16* YC, const float* LPA, const float* kmax_l, LAS char* vt, int wave, int lane) {
;     ...
;     A_STAGE(sA, R0, 0); A_LOAD(R0, 3);
;     A_STAGE(sB, R1, 1); A_LOAD(R1, 4);
;     fb_update(o, ol, sA[0], sA[1], vt, lane);
;     A_STAGE(sA, R2, 2); A_LOAD(R2, 5);
;     fb_update(o, ol, sB[0], sB[1], vt + A_V1, lane);
;     A_STAGE(sB, R0, 3); A_LOAD(R0, 6);
;     fb_update(o, ol, sA[0], sA[1], vt, lane);
;     A_STAGE(sA, R1, 4); A_LOAD(R1, 7);
;     fb_update(o, ol, sB[0], sB[1], vt + A_V1, lane);
	ds_write_b128 v183, v[24:27]
	ds_write_b128 v183, v[20:23] offset:9216
	s_waitcnt vmcnt(20)
	ds_write_b128 v183, v[32:35] offset:1152
	ds_write_b128 v183, v[28:31] offset:10368
	s_waitcnt vmcnt(18)
	ds_write_b128 v183, v[40:43] offset:2304
	ds_write_b128 v183, v[36:39] offset:11520
	s_waitcnt vmcnt(16)
	ds_write_b128 v183, v[48:51] offset:3456
	ds_write_b128 v183, v[44:47] offset:12672
	v_or_b32_e32 v20, s1, v167
	v_sub_u32_e32 v28, v20, v154
	ds_read_b128 v[20:23], v151 offset:9216
	ds_read_b128 v[24:27], v151 offset:9280
	s_waitcnt lgkmcnt(1)
	v_mfma_f32_16x16x32_bf16 v[20:23], v[20:23], v[8:11], v[12:15]
	v_cvt_pk_bf16_f32 v140, v16, v18
	v_cvt_pk_bf16_f32 v142, v17, v19
	v_mov_b64_e32 v[16:17], s[84:85]
	s_waitcnt lgkmcnt(0)
	v_mfma_f32_16x16x32_bf16 v[20:23], v[24:27], v[4:7], v[20:23]
	v_add_u32_e32 v24, 0x400, v28
	v_mov_b64_e32 v[18:19], s[86:87]
	v_cmp_gt_u32_e32 vcc, s14, v24
	v_cvt_f32_i32_e32 v24, v28
	v_cvt_pk_bf16_f32 v141, v116, v118
	v_cvt_pk_bf16_f32 v143, v117, v119
	v_add_u32_e32 v36, s33, v180
	s_nop 0
	v_fma_f32 v20, |v24|, v153, v20
	v_mfma_f32_16x16x32_bf16 v[116:119], v[16:19], v[140:143], 0
	v_add_u32_e32 v24, 0x410, v28
	v_med3_i32 v36, v36, 0, v233
	v_add_u32_e32 v44, s33, v181
	v_mfma_f32_16x16x32_bf16 v[120:123], v[120:123], v[140:143], 0
	v_exp_f32_e32 v137, v137
	v_exp_f32_e32 v138, v138
	v_exp_f32_e32 v139, v139
	v_mfma_f32_16x16x32_bf16 v[124:127], v[124:127], v[140:143], 0
	v_med3_i32 v44, v44, 0, v233
	v_cvt_pk_bf16_f32 v200, v136, v137
	v_cvt_pk_bf16_f32 v201, v138, v139
	v_mfma_f32_16x16x32_bf16 v[132:135], v[132:135], v[140:143], 0
	v_mfma_f32_16x16x32_bf16 v[140:143], v[144:147], v[140:143], 0
	v_cndmask_b32_e32 v144, v234, v20, vcc
	v_add_u32_e32 v20, 16, v28
	v_cvt_f32_i32_e32 v20, v20
	v_cmp_gt_u32_e32 vcc, s14, v24
	ds_read_b128 v[24:27], v151 offset:11584
	v_mfma_f32_16x16x32_bf16 v[116:119], v[16:19], v[198:201], v[116:119]
	v_fma_f32 v20, |v20|, v153, v21
	v_cndmask_b32_e32 v145, v234, v20, vcc
	v_add_u32_e32 v20, 32, v28
	v_cvt_f32_i32_e32 v20, v20
	v_add_u32_e32 v21, 0x420, v28
	v_cmp_gt_u32_e32 vcc, s14, v21
	v_add_u32_e32 v21, 0x430, v28
	v_fma_f32 v20, |v20|, v153, v22
	v_cndmask_b32_e32 v146, v234, v20, vcc
	v_add_u32_e32 v20, 48, v28
	v_cvt_f32_i32_e32 v20, v20
	v_cmp_gt_u32_e32 vcc, s14, v21
	v_fma_f32 v20, |v20|, v153, v23
	s_nop 0
	v_cndmask_b32_e32 v147, v234, v20, vcc
	ds_read_b128 v[20:23], v151 offset:11520
	s_waitcnt lgkmcnt(0)
	v_mfma_f32_16x16x32_bf16 v[20:23], v[20:23], v[8:11], v[12:15]
	v_mfma_f32_16x16x32_bf16 v[20:23], v[24:27], v[4:7], v[20:23]
	v_add_u32_e32 v24, 0x100, v28
	v_cvt_f32_i32_e32 v24, v24
	v_add_u32_e32 v25, 0x500, v28
	v_cmp_gt_u32_e32 vcc, s14, v25
	s_nop 3
	v_fma_f32 v20, |v24|, v153, v20
	v_cndmask_b32_e32 v155, v234, v20, vcc
	v_add_u32_e32 v20, 0x110, v28
	v_cvt_f32_i32_e32 v20, v20
	v_add_u32_e32 v24, 0x510, v28
	v_cmp_gt_u32_e32 vcc, s14, v24
	v_fma_f32 v20, |v20|, v153, v21
	s_nop 0
	v_cndmask_b32_e32 v186, v234, v20, vcc
	v_add_u32_e32 v20, 0x120, v28
	v_cvt_f32_i32_e32 v20, v20
	v_add_u32_e32 v21, 0x520, v28
	v_cmp_gt_u32_e32 vcc, s14, v21
	v_add_u32_e32 v21, 0x530, v28
	v_fma_f32 v20, |v20|, v153, v22
	v_cndmask_b32_e32 v187, v234, v20, vcc
	v_add_u32_e32 v20, 0x130, v28
	v_cvt_f32_i32_e32 v20, v20
	v_cmp_gt_u32_e32 vcc, s14, v21
	v_add_u32_e32 v28, s33, v179
	v_med3_i32 v28, v28, 0, v233
	v_fma_f32 v20, |v20|, v153, v23
	v_cndmask_b32_e32 v191, v234, v20, vcc
	v_add_u32_e32 v20, s33, v178
	v_med3_i32 v20, v20, 0, v233
	v_lshlrev_b32_e32 v188, 7, v20
	v_lshl_add_u64 v[20:21], v[156:157], 0, v[188:189]
	v_lshl_add_u64 v[24:25], v[158:159], 0, v[188:189]
	v_lshlrev_b32_e32 v188, 7, v28
	v_lshl_add_u64 v[28:29], v[156:157], 0, v[188:189]
	v_lshl_add_u64 v[32:33], v[158:159], 0, v[188:189]
	v_lshlrev_b32_e32 v188, 7, v36
	v_lshl_add_u64 v[36:37], v[156:157], 0, v[188:189]
	v_lshl_add_u64 v[40:41], v[158:159], 0, v[188:189]
	v_lshlrev_b32_e32 v188, 7, v44
	v_lshl_add_u64 v[44:45], v[156:157], 0, v[188:189]
	v_lshl_add_u64 v[48:49], v[158:159], 0, v[188:189]
	global_load_dwordx4 v[20:23], v[20:21], off
	s_nop 0
	global_load_dwordx4 v[24:27], v[24:25], off
	s_nop 0
	global_load_dwordx4 v[28:31], v[28:29], off
	s_nop 0
	global_load_dwordx4 v[32:35], v[32:33], off
	s_nop 0
	global_load_dwordx4 v[36:39], v[36:37], off
	s_nop 0
	global_load_dwordx4 v[40:43], v[40:41], off
	s_nop 0
	global_load_dwordx4 v[44:47], v[44:45], off
	s_nop 0
	global_load_dwordx4 v[48:51], v[48:49], off
	ds_read_b64_tr_b16 v[130:131], v184 offset:6912
	ds_read_b64_tr_b16 v[128:129], v184 offset:4608
	ds_read_b64_tr_b16 v[136:137], v184 offset:4640
	ds_read_b64_tr_b16 v[138:139], v184 offset:6944
	s_waitcnt lgkmcnt(2)
	v_mfma_f32_16x16x32_bf16 v[120:123], v[128:131], v[198:201], v[120:123]
	s_waitcnt lgkmcnt(0)
	v_mfma_f32_16x16x32_bf16 v[128:131], v[136:139], v[198:201], v[124:127]
	s_nop 2
	ds_read_b64_tr_b16 v[124:125], v184 offset:4672
	ds_read_b64_tr_b16 v[126:127], v184 offset:6976
	s_waitcnt lgkmcnt(0)
	v_mfma_f32_16x16x32_bf16 v[136:139], v[124:127], v[198:201], v[132:135]
	ds_read_b64_tr_b16 v[124:125], v184 offset:4704
	ds_read_b64_tr_b16 v[126:127], v184 offset:7008
	s_waitcnt vmcnt(22)
	ds_write_b128 v183, v[56:59] offset:4608
	ds_write_b128 v183, v[52:55] offset:9216
	s_waitcnt vmcnt(20)
	ds_write_b128 v183, v[64:67] offset:5760
	ds_write_b128 v183, v[60:63] offset:10368
	s_waitcnt vmcnt(18)
	ds_write_b128 v183, v[72:75] offset:6912
	ds_write_b128 v183, v[68:71] offset:11520
	s_waitcnt vmcnt(16)
	ds_write_b128 v183, v[80:83] offset:8064
	ds_write_b128 v183, v[76:79] offset:12672
	v_or_b32_e32 v52, s4, v167
	v_sub_u32_e32 v60, v52, v154
	ds_read_b128 v[52:55], v151 offset:9216
	ds_read_b128 v[56:59], v151 offset:9280
	s_waitcnt lgkmcnt(1)
; #define A_LOAD(R, t_) do { int tb_, sd_, md_; a_desc((t_), a0, rho, tb_, sd_, md_); tile_load(R, kb, vb, tb_, sd_, lane); } while (0)
; #define A_STAGE(S, R, t_) do { int tb_, sd_, md_; a_desc((t_), a0, rho, tb_, sd_, md_); a_stage(S, R, vt, (t_) & 1, qf, cinit, tb_, sd_, md_, tq, nslope2, lane); } while (0)
; DI void mixerA2_unit(int u, const bf16* PROJ, bf16* YC, const float* LPA, const float* kmax_l, LAS char* vt, int wave, int lane) {
;     ...
;     A_STAGE(sA, R2, 2); A_LOAD(R2, 5);
;     fb_update(o, ol, sB[0], sB[1], vt + A_V1, lane);
;     A_STAGE(sB, R0, 3); A_LOAD(R0, 6);
;     fb_update(o, ol, sA[0], sA[1], vt, lane);
;     A_STAGE(sA, R1, 4); A_LOAD(R1, 7);
;     fb_update(o, ol, sB[0], sB[1], vt + A_V1, lane);
;     A_STAGE(sB, R2, 5); A_LOAD(R2, 8);
;     fb_update(o, ol, sA[0], sA[1], vt, lane);
;     A_STAGE(sA, R0, 6); A_LOAD(R0, 9);
	v_mfma_f32_16x16x32_bf16 v[52:55], v[52:55], v[8:11], v[12:15]
	s_or_b32 s4, s5, s62
	v_add_u32_e32 v68, s4, v180
	v_exp_f32_e32 v132, v146
	s_waitcnt lgkmcnt(0)
	v_mfma_f32_16x16x32_bf16 v[52:55], v[56:59], v[4:7], v[52:55]
	v_add_u32_e32 v56, 0x400, v60
	v_cmp_gt_u32_e32 vcc, s14, v56
	v_cvt_f32_i32_e32 v56, v60
	v_mfma_f32_16x16x32_bf16 v[140:143], v[124:127], v[198:201], v[140:143]
	v_exp_f32_e32 v124, v144
	v_exp_f32_e32 v125, v155
	s_nop 1
	v_fma_f32 v52, |v56|, v153, v52
	v_cndmask_b32_e32 v193, v234, v52, vcc
	v_add_u32_e32 v52, 16, v60
	v_cvt_f32_i32_e32 v52, v52
	v_add_u32_e32 v56, 0x410, v60
	v_cmp_gt_u32_e32 vcc, s14, v56
	ds_read_b128 v[56:59], v151 offset:11584
	v_fma_f32 v52, |v52|, v153, v53
	v_cndmask_b32_e32 v198, v234, v52, vcc
	v_add_u32_e32 v52, 32, v60
	v_cvt_f32_i32_e32 v52, v52
	v_add_u32_e32 v53, 0x420, v60
	v_cmp_gt_u32_e32 vcc, s14, v53
	v_add_u32_e32 v53, 0x430, v60
	v_fma_f32 v52, |v52|, v153, v54
	v_cndmask_b32_e32 v199, v234, v52, vcc
	v_add_u32_e32 v52, 48, v60
	v_cvt_f32_i32_e32 v52, v52
	v_cmp_gt_u32_e32 vcc, s14, v53
	v_exp_f32_e32 v126, v145
	v_exp_f32_e32 v127, v186
	v_fma_f32 v52, |v52|, v153, v55
	v_cndmask_b32_e32 v200, v234, v52, vcc
	ds_read_b128 v[52:55], v151 offset:11520
	s_waitcnt lgkmcnt(0)
	v_mfma_f32_16x16x32_bf16 v[52:55], v[52:55], v[8:11], v[12:15]
	v_exp_f32_e32 v133, v187
	v_exp_f32_e32 v134, v147
	v_exp_f32_e32 v135, v191
	v_mfma_f32_16x16x32_bf16 v[52:55], v[56:59], v[4:7], v[52:55]
	v_add_u32_e32 v56, 0x100, v60
	v_cvt_f32_i32_e32 v56, v56
	v_add_u32_e32 v57, 0x500, v60
	v_cmp_gt_u32_e32 vcc, s14, v57
	v_med3_i32 v68, v68, 0, v233
	s_nop 2
	v_fma_f32 v52, |v56|, v153, v52
	v_cndmask_b32_e32 v201, v234, v52, vcc
	v_add_u32_e32 v52, 0x110, v60
	v_cvt_f32_i32_e32 v52, v52
	v_add_u32_e32 v56, 0x510, v60
	v_cmp_gt_u32_e32 vcc, s14, v56
	v_add_u32_e32 v76, s4, v181
	v_fma_f32 v52, |v52|, v153, v53
	v_cndmask_b32_e32 v202, v234, v52, vcc
	v_add_u32_e32 v52, 0x120, v60
	v_cvt_f32_i32_e32 v52, v52
	v_add_u32_e32 v53, 0x520, v60
	v_cmp_gt_u32_e32 vcc, s14, v53
	v_add_u32_e32 v53, 0x530, v60
	v_fma_f32 v52, |v52|, v153, v54
	v_cndmask_b32_e32 v203, v234, v52, vcc
	v_add_u32_e32 v52, 0x130, v60
	v_cvt_f32_i32_e32 v52, v52
	v_cmp_gt_u32_e32 vcc, s14, v53
	v_add_u32_e32 v60, s4, v179
	v_med3_i32 v60, v60, 0, v233
	v_fma_f32 v52, |v52|, v153, v55
	v_cndmask_b32_e32 v204, v234, v52, vcc
	v_add_u32_e32 v52, s4, v178
	v_med3_i32 v52, v52, 0, v233
	v_lshlrev_b32_e32 v188, 7, v52
	v_lshl_add_u64 v[52:53], v[156:157], 0, v[188:189]
	v_lshl_add_u64 v[56:57], v[158:159], 0, v[188:189]
	v_lshlrev_b32_e32 v188, 7, v60
	v_lshl_add_u64 v[60:61], v[156:157], 0, v[188:189]
	v_lshl_add_u64 v[64:65], v[158:159], 0, v[188:189]
	v_lshlrev_b32_e32 v188, 7, v68
	v_med3_i32 v76, v76, 0, v233
	v_lshl_add_u64 v[68:69], v[156:157], 0, v[188:189]
	v_lshl_add_u64 v[72:73], v[158:159], 0, v[188:189]
	v_lshlrev_b32_e32 v188, 7, v76
	v_lshl_add_u64 v[76:77], v[156:157], 0, v[188:189]
	v_lshl_add_u64 v[80:81], v[158:159], 0, v[188:189]
	v_cvt_pk_bf16_f32 v144, v124, v126
	v_cvt_pk_bf16_f32 v145, v132, v134
	v_cvt_pk_bf16_f32 v146, v125, v127
	v_cvt_pk_bf16_f32 v147, v133, v135
	global_load_dwordx4 v[52:55], v[52:53], off
	s_or_b32 s16, s4, 0x80
	global_load_dwordx4 v[56:59], v[56:57], off
	v_mfma_f32_16x16x32_bf16 v[132:135], v[16:19], v[144:147], v[116:119]
	global_load_dwordx4 v[60:63], v[60:61], off
	s_nop 0
	global_load_dwordx4 v[64:67], v[64:65], off
	s_nop 0
	global_load_dwordx4 v[68:71], v[68:69], off
	s_nop 0
	global_load_dwordx4 v[72:75], v[72:73], off
	s_nop 0
	global_load_dwordx4 v[76:79], v[76:77], off
	s_nop 0
	global_load_dwordx4 v[80:83], v[80:81], off
	ds_read_b64_tr_b16 v[118:119], v184 offset:2304
	ds_read_b64_tr_b16 v[116:117], v184
	ds_read_b64_tr_b16 v[206:207], v184 offset:32
	s_waitcnt lgkmcnt(1)
	v_mfma_f32_16x16x32_bf16 v[124:127], v[116:119], v[144:147], v[120:123]
	ds_read_b64_tr_b16 v[208:209], v184 offset:2336
	ds_read_b64_tr_b16 v[116:117], v184 offset:64
	ds_read_b64_tr_b16 v[118:119], v184 offset:2368
	s_waitcnt lgkmcnt(0)
	v_mfma_f32_16x16x32_bf16 v[120:123], v[116:119], v[144:147], v[136:139]
	ds_read_b64_tr_b16 v[116:117], v184 offset:96
	ds_read_b64_tr_b16 v[118:119], v184 offset:2400
	s_waitcnt vmcnt(22)
	ds_write_b128 v183, v[88:91]
	ds_write_b128 v183, v[84:87] offset:9216
	s_waitcnt vmcnt(20)
	ds_write_b128 v183, v[96:99] offset:1152
	ds_write_b128 v183, v[92:95] offset:10368
	s_waitcnt vmcnt(18)
	ds_write_b128 v183, v[104:107] offset:2304
	ds_write_b128 v183, v[100:103] offset:11520
	s_waitcnt vmcnt(16)
	ds_write_b128 v183, v[112:115] offset:3456
	ds_write_b128 v183, v[108:111] offset:12672
	ds_read_b128 v[84:87], v151 offset:9216
	ds_read_b128 v[88:91], v151 offset:9280
	s_waitcnt lgkmcnt(1)
	v_mfma_f32_16x16x32_bf16 v[84:87], v[84:87], v[8:11], v[12:15]
	v_or_b32_e32 v92, s0, v168
	v_sub_u32_e32 v93, v92, v154
	v_cmp_gt_u32_e64 s[0:1], s67, v92
	s_waitcnt lgkmcnt(0)
	v_mfma_f32_16x16x32_bf16 v[84:87], v[88:91], v[4:7], v[84:87]
	v_add_u32_e32 v88, 0x100, v93
	v_cmp_gt_u32_e32 vcc, s22, v88
	v_cvt_f32_i32_e32 v88, v93
	s_and_b64 vcc, s[54:55], vcc
	v_mfma_f32_16x16x32_bf16 v[128:131], v[206:209], v[144:147], v[128:131]
	v_exp_f32_e32 v136, v193
	s_nop 1
	v_fma_f32 v84, |v88|, v153, v84
	v_add_u32_e32 v88, 0x104, v93
	v_mfma_f32_16x16x32_bf16 v[116:119], v[116:119], v[144:147], v[140:143]
	v_cndmask_b32_e32 v144, v234, v84, vcc
	v_add_u32_e32 v84, 4, v93
	v_cvt_f32_i32_e32 v84, v84
	v_cmp_gt_u32_e32 vcc, s22, v88
	s_and_b64 vcc, vcc, s[0:1]
	v_cmp_gt_u32_e64 s[0:1], s23, v92
	v_fma_f32 v84, |v84|, v153, v85
	v_cndmask_b32_e32 v145, v234, v84, vcc
	v_add_u32_e32 v84, 8, v93
	v_cvt_f32_i32_e32 v84, v84
	v_add_u32_e32 v85, 0x108, v93
	v_cmp_gt_u32_e32 vcc, s22, v85
	s_and_b64 vcc, vcc, s[0:1]
	v_fma_f32 v84, |v84|, v153, v86
	v_cndmask_b32_e32 v146, v234, v84, vcc
	v_add_u32_e32 v84, 12, v93
	v_cvt_f32_i32_e32 v84, v84
	v_add_u32_e32 v85, 0x10c, v93
	v_cmp_gt_u32_e32 vcc, s22, v85
	v_cmp_gt_u32_e64 s[0:1], s17, v92
	s_and_b64 vcc, vcc, s[0:1]
	v_fma_f32 v84, |v84|, v153, v87
	v_cndmask_b32_e32 v147, v234, v84, vcc
	ds_read_b128 v[84:87], v151 offset:11520
	ds_read_b128 v[88:91], v151 offset:11584
	s_waitcnt lgkmcnt(1)
; #define A_LOAD(R, t_) do { int tb_, sd_, md_; a_desc((t_), a0, rho, tb_, sd_, md_); tile_load(R, kb, vb, tb_, sd_, lane); } while (0)
; #define A_STAGE(S, R, t_) do { int tb_, sd_, md_; a_desc((t_), a0, rho, tb_, sd_, md_); a_stage(S, R, vt, (t_) & 1, qf, cinit, tb_, sd_, md_, tq, nslope2, lane); } while (0)
; DI void mixerA2_unit(int u, const bf16* PROJ, bf16* YC, const float* LPA, const float* kmax_l, LAS char* vt, int wave, int lane) {
;     ...
;     A_STAGE(sB, R0, 3); A_LOAD(R0, 6);
;     fb_update(o, ol, sA[0], sA[1], vt, lane);
;     A_STAGE(sA, R1, 4); A_LOAD(R1, 7);
;     fb_update(o, ol, sB[0], sB[1], vt + A_V1, lane);
;     A_STAGE(sB, R2, 5); A_LOAD(R2, 8);
;     fb_update(o, ol, sA[0], sA[1], vt, lane);
;     A_STAGE(sA, R0, 6); A_LOAD(R0, 9);
	v_mfma_f32_16x16x32_bf16 v[84:87], v[84:87], v[8:11], v[12:15]
	v_cmp_gt_u32_e64 s[0:1], s58, v92
	v_exp_f32_e32 v138, v201
	v_exp_f32_e32 v137, v198
	s_waitcnt lgkmcnt(0)
	v_mfma_f32_16x16x32_bf16 v[84:87], v[88:91], v[4:7], v[84:87]
	v_add_u32_e32 v88, 64, v93
	v_cvt_f32_i32_e32 v88, v88
	v_add_u32_e32 v89, 0x140, v93
	v_cmp_gt_u32_e32 vcc, s22, v89
	s_and_b64 vcc, s[54:55], vcc
	s_nop 2
	v_fma_f32 v84, |v88|, v153, v84
	v_cndmask_b32_e32 v155, v234, v84, vcc
	v_add_u32_e32 v84, 0x44, v93
	v_cvt_f32_i32_e32 v84, v84
	v_add_u32_e32 v88, 0x144, v93
	v_cmp_gt_u32_e32 vcc, s22, v88
	s_and_b64 vcc, vcc, s[0:1]
	v_fma_f32 v84, |v84|, v153, v85
	v_cndmask_b32_e32 v186, v234, v84, vcc
	v_add_u32_e32 v84, 0x48, v93
	v_cvt_f32_i32_e32 v84, v84
	v_add_u32_e32 v85, 0x148, v93
	v_cmp_gt_u32_e32 vcc, s22, v85
	v_cmp_gt_u32_e64 s[0:1], s59, v92
	s_and_b64 vcc, vcc, s[0:1]
	v_fma_f32 v84, |v84|, v153, v86
	v_cndmask_b32_e32 v187, v234, v84, vcc
	v_add_u32_e32 v84, 0x4c, v93
	v_cvt_f32_i32_e32 v84, v84
	v_add_u32_e32 v85, 0x14c, v93
	v_cmp_gt_u32_e32 vcc, s22, v85
	v_cmp_gt_u32_e64 s[0:1], s52, v92
	s_and_b64 vcc, vcc, s[0:1]
	v_fma_f32 v84, |v84|, v153, v87
	v_cndmask_b32_e32 v191, v234, v84, vcc
	v_add_u32_e32 v84, s16, v178
	v_med3_i32 v84, v84, 0, v233
	v_lshlrev_b32_e32 v188, 7, v84
	v_lshl_add_u64 v[84:85], v[156:157], 0, v[188:189]
	global_load_dwordx4 v[108:111], v[84:85], off
	v_lshl_add_u64 v[84:85], v[158:159], 0, v[188:189]
	global_load_dwordx4 v[112:115], v[84:85], off
	v_add_u32_e32 v84, s16, v179
	v_med3_i32 v84, v84, 0, v233
	v_lshlrev_b32_e32 v188, 7, v84
	v_lshl_add_u64 v[84:85], v[156:157], 0, v[188:189]
	global_load_dwordx4 v[100:103], v[84:85], off
	v_lshl_add_u64 v[84:85], v[158:159], 0, v[188:189]
	global_load_dwordx4 v[104:107], v[84:85], off
	v_add_u32_e32 v84, s16, v180
	v_med3_i32 v84, v84, 0, v233
	v_lshlrev_b32_e32 v188, 7, v84
	v_lshl_add_u64 v[84:85], v[156:157], 0, v[188:189]
	global_load_dwordx4 v[92:95], v[84:85], off
	v_lshl_add_u64 v[84:85], v[158:159], 0, v[188:189]
	global_load_dwordx4 v[96:99], v[84:85], off
	v_add_u32_e32 v84, s16, v181
	v_exp_f32_e32 v139, v202
	v_exp_f32_e32 v140, v199
	v_exp_f32_e32 v141, v203
	v_exp_f32_e32 v142, v200
	v_exp_f32_e32 v143, v204
	v_med3_i32 v84, v84, 0, v233
	v_lshlrev_b32_e32 v188, 7, v84
	v_lshl_add_u64 v[84:85], v[156:157], 0, v[188:189]
	v_lshl_add_u64 v[88:89], v[158:159], 0, v[188:189]
	global_load_dwordx4 v[84:87], v[84:85], off
	v_cvt_pk_bf16_f32 v136, v136, v137
	global_load_dwordx4 v[88:91], v[88:89], off
	v_cvt_pk_bf16_f32 v137, v140, v142
	v_cvt_pk_bf16_f32 v138, v138, v139
	v_cvt_pk_bf16_f32 v139, v141, v143
	ds_read_b64_tr_b16 v[142:143], v184 offset:6912
	ds_read_b64_tr_b16 v[140:141], v184 offset:4608
	ds_read_b64_tr_b16 v[198:199], v184 offset:4640
	s_waitcnt lgkmcnt(1)
	v_mfma_f32_16x16x32_bf16 v[124:127], v[140:143], v[136:139], v[124:127]
	ds_read_b64_tr_b16 v[200:201], v184 offset:6944
	ds_read_b64_tr_b16 v[140:141], v184 offset:4672
	ds_read_b64_tr_b16 v[142:143], v184 offset:6976
	s_waitcnt lgkmcnt(0)
	v_mfma_f32_16x16x32_bf16 v[140:143], v[140:143], v[136:139], v[120:123]
	s_nop 2
	ds_read_b64_tr_b16 v[120:121], v184 offset:4704
	ds_read_b64_tr_b16 v[122:123], v184 offset:7008
	s_waitcnt vmcnt(22)
	ds_write_b128 v183, v[24:27] offset:4608
	ds_write_b128 v183, v[20:23] offset:9216
	s_waitcnt vmcnt(20)
	ds_write_b128 v183, v[32:35] offset:5760
	ds_write_b128 v183, v[28:31] offset:10368
	s_waitcnt vmcnt(18)
	ds_write_b128 v183, v[40:43] offset:6912
	ds_write_b128 v183, v[36:39] offset:11520
	s_waitcnt vmcnt(16)
	ds_write_b128 v183, v[48:51] offset:8064
	ds_write_b128 v183, v[44:47] offset:12672
	ds_read_b128 v[20:23], v151 offset:9216
	ds_read_b128 v[24:27], v151 offset:9280
	s_waitcnt lgkmcnt(1)
	v_mfma_f32_16x16x32_bf16 v[20:23], v[20:23], v[8:11], v[12:15]
	v_or_b32_e32 v28, s33, v168
	v_sub_u32_e32 v29, v28, v154
	v_cmp_gt_u32_e64 s[0:1], s67, v28
	s_waitcnt lgkmcnt(0)
	v_mfma_f32_16x16x32_bf16 v[20:23], v[24:27], v[4:7], v[20:23]
	v_add_u32_e32 v24, 0x100, v29
	v_cmp_gt_u32_e32 vcc, s22, v24
	v_cvt_f32_i32_e32 v24, v29
	s_and_b64 vcc, s[90:91], vcc
	v_mfma_f32_16x16x32_bf16 v[128:131], v[198:201], v[136:139], v[128:131]
	s_or_b32 s33, s5, s65
	s_nop 1
	v_fma_f32 v20, |v24|, v153, v20
	v_cndmask_b32_e32 v193, v234, v20, vcc
	v_add_u32_e32 v20, 4, v29
	v_cvt_f32_i32_e32 v20, v20
	v_add_u32_e32 v24, 0x104, v29
	v_cmp_gt_u32_e32 vcc, s22, v24
	s_and_b64 vcc, vcc, s[0:1]
	v_fma_f32 v20, |v20|, v153, v21
	v_cndmask_b32_e32 v198, v234, v20, vcc
	v_add_u32_e32 v20, 8, v29
	v_cvt_f32_i32_e32 v20, v20
	v_add_u32_e32 v21, 0x108, v29
	v_cmp_gt_u32_e32 vcc, s22, v21
	v_cmp_gt_u32_e64 s[0:1], s23, v28
	s_and_b64 vcc, vcc, s[0:1]
	v_fma_f32 v20, |v20|, v153, v22
	v_cndmask_b32_e32 v199, v234, v20, vcc
	v_add_u32_e32 v20, 12, v29
	v_cvt_f32_i32_e32 v20, v20
	v_add_u32_e32 v21, 0x10c, v29
	v_cmp_gt_u32_e32 vcc, s22, v21
	v_cmp_gt_u32_e64 s[0:1], s17, v28
	s_and_b64 vcc, vcc, s[0:1]
	v_fma_f32 v20, |v20|, v153, v23
	v_cndmask_b32_e32 v200, v234, v20, vcc
	ds_read_b128 v[20:23], v151 offset:11520
	ds_read_b128 v[24:27], v151 offset:11584
	s_waitcnt lgkmcnt(1)
	v_mfma_f32_16x16x32_bf16 v[20:23], v[20:23], v[8:11], v[12:15]
	v_add_u32_e32 v32, s33, v181
	v_med3_i32 v32, v32, 0, v233
	s_or_b32 s5, s5, s68
	s_waitcnt lgkmcnt(0)
; #define A_LOAD(R, t_) do { int tb_, sd_, md_; a_desc((t_), a0, rho, tb_, sd_, md_); tile_load(R, kb, vb, tb_, sd_, lane); } while (0)
; #define A_STAGE(S, R, t_) do { int tb_, sd_, md_; a_desc((t_), a0, rho, tb_, sd_, md_); a_stage(S, R, vt, (t_) & 1, qf, cinit, tb_, sd_, md_, tq, nslope2, lane); } while (0)
; DI void mixerA2_unit(int u, const bf16* PROJ, bf16* YC, const float* LPA, const float* kmax_l, LAS char* vt, int wave, int lane) {
;     ...
;     A_STAGE(sA, R1, 4); A_LOAD(R1, 7);
;     fb_update(o, ol, sB[0], sB[1], vt + A_V1, lane);
;     A_STAGE(sB, R2, 5); A_LOAD(R2, 8);
;     fb_update(o, ol, sA[0], sA[1], vt, lane);
;     A_STAGE(sA, R0, 6); A_LOAD(R0, 9);
;     fb_update(o, ol, sB[0], sB[1], vt + A_V1, lane);
;     A_STAGE(sB, R1, 7);
	v_mfma_f32_16x16x32_bf16 v[20:23], v[24:27], v[4:7], v[20:23]
	v_add_u32_e32 v24, 64, v29
	v_cvt_f32_i32_e32 v24, v24
	v_add_u32_e32 v25, 0x140, v29
	v_cmp_gt_u32_e32 vcc, s22, v25
	s_and_b64 vcc, s[90:91], vcc
	s_nop 2
	v_fma_f32 v20, |v24|, v153, v20
	v_cndmask_b32_e32 v201, v234, v20, vcc
	v_add_u32_e32 v20, 0x44, v29
	v_cvt_f32_i32_e32 v20, v20
	v_add_u32_e32 v24, 0x144, v29
	v_cmp_gt_u32_e32 vcc, s22, v24
	v_add_u32_e32 v24, 0x44, v28
	v_cmp_gt_u32_e64 s[0:1], s24, v24
	s_and_b64 vcc, vcc, s[0:1]
	v_fma_f32 v20, |v20|, v153, v21
	v_cndmask_b32_e32 v202, v234, v20, vcc
	v_add_u32_e32 v20, 0x48, v29
	v_cvt_f32_i32_e32 v20, v20
	v_add_u32_e32 v21, 0x148, v29
	v_cmp_gt_u32_e32 vcc, s22, v21
	v_add_u32_e32 v21, 0x48, v28
	v_cmp_gt_u32_e64 s[0:1], s24, v21
	s_and_b64 vcc, vcc, s[0:1]
	v_fma_f32 v20, |v20|, v153, v22
	v_cndmask_b32_e32 v203, v234, v20, vcc
	v_add_u32_e32 v20, 0x4c, v29
	v_cvt_f32_i32_e32 v20, v20
	v_add_u32_e32 v21, 0x14c, v29
	v_cmp_gt_u32_e32 vcc, s22, v21
	v_add_u32_e32 v21, 0x4c, v28
	v_cmp_gt_u32_e64 s[0:1], s24, v21
	s_and_b64 vcc, vcc, s[0:1]
	v_fma_f32 v20, |v20|, v153, v23
	v_cndmask_b32_e32 v204, v234, v20, vcc
	v_add_u32_e32 v20, s33, v178
	v_med3_i32 v20, v20, 0, v233
	v_lshlrev_b32_e32 v188, 7, v20
	v_lshl_add_u64 v[20:21], v[156:157], 0, v[188:189]
	global_load_dwordx4 v[44:47], v[20:21], off
	v_lshl_add_u64 v[20:21], v[158:159], 0, v[188:189]
	global_load_dwordx4 v[48:51], v[20:21], off
	v_add_u32_e32 v20, s33, v179
	v_med3_i32 v20, v20, 0, v233
	v_lshlrev_b32_e32 v188, 7, v20
	v_lshl_add_u64 v[20:21], v[156:157], 0, v[188:189]
	v_lshl_add_u64 v[24:25], v[158:159], 0, v[188:189]
	v_mfma_f32_16x16x32_bf16 v[132:135], v[16:19], v[136:139], v[132:135]
	global_load_dwordx4 v[20:23], v[20:21], off
	s_nop 0
	global_load_dwordx4 v[36:39], v[24:25], off
	v_mfma_f32_16x16x32_bf16 v[116:119], v[120:123], v[136:139], v[116:119]
	v_add_u32_e32 v24, s33, v180
	v_exp_f32_e32 v120, v144
	v_exp_f32_e32 v121, v155
	v_exp_f32_e32 v122, v145
	v_exp_f32_e32 v123, v186
	v_exp_f32_e32 v136, v146
	v_exp_f32_e32 v137, v187
	v_exp_f32_e32 v138, v147
	v_exp_f32_e32 v139, v191
	v_med3_i32 v24, v24, 0, v233
	v_lshlrev_b32_e32 v188, 7, v24
	v_lshl_add_u64 v[24:25], v[156:157], 0, v[188:189]
	v_lshl_add_u64 v[28:29], v[158:159], 0, v[188:189]
	v_lshlrev_b32_e32 v188, 7, v32
	v_lshl_add_u64 v[32:33], v[156:157], 0, v[188:189]
	v_lshl_add_u64 v[40:41], v[158:159], 0, v[188:189]
	v_cvt_pk_bf16_f32 v144, v120, v122
	v_cvt_pk_bf16_f32 v145, v136, v138
	v_cvt_pk_bf16_f32 v146, v121, v123
	v_cvt_pk_bf16_f32 v147, v137, v139
	global_load_dwordx4 v[24:27], v[24:25], off
	s_nop 0
	global_load_dwordx4 v[28:31], v[28:29], off
	v_mfma_f32_16x16x32_bf16 v[136:139], v[16:19], v[144:147], v[132:135]
	global_load_dwordx4 v[32:35], v[32:33], off
	s_nop 0
	global_load_dwordx4 v[40:43], v[40:41], off
	ds_read_b64_tr_b16 v[122:123], v184 offset:2304
	ds_read_b64_tr_b16 v[120:121], v184
	ds_read_b64_tr_b16 v[132:133], v184 offset:32
	ds_read_b64_tr_b16 v[134:135], v184 offset:2336
	s_waitcnt lgkmcnt(2)
	v_mfma_f32_16x16x32_bf16 v[120:123], v[120:123], v[144:147], v[124:127]
	s_waitcnt lgkmcnt(0)
	v_mfma_f32_16x16x32_bf16 v[124:127], v[132:135], v[144:147], v[128:131]
	s_nop 2
	ds_read_b64_tr_b16 v[128:129], v184 offset:64
	ds_read_b64_tr_b16 v[130:131], v184 offset:2368
	ds_read_b64_tr_b16 v[132:133], v184 offset:96
	ds_read_b64_tr_b16 v[134:135], v184 offset:2400
	s_waitcnt vmcnt(22)
	ds_write_b128 v183, v[56:59]
	ds_write_b128 v183, v[52:55] offset:9216
	s_waitcnt vmcnt(20)
	ds_write_b128 v183, v[64:67] offset:1152
	ds_write_b128 v183, v[60:63] offset:10368
	s_waitcnt vmcnt(18)
	ds_write_b128 v183, v[72:75] offset:2304
	ds_write_b128 v183, v[68:71] offset:11520
	s_waitcnt vmcnt(16)
	ds_write_b128 v183, v[80:83] offset:3456
	ds_write_b128 v183, v[76:79] offset:12672
	ds_read_b128 v[52:55], v151 offset:9216
	ds_read_b128 v[56:59], v151 offset:9280
	s_waitcnt lgkmcnt(1)
	v_mfma_f32_16x16x32_bf16 v[52:55], v[52:55], v[8:11], v[12:15]
	v_or_b32_e32 v60, s4, v168
	v_sub_u32_e32 v61, v60, v154
	v_cmp_gt_u32_e64 s[0:1], s67, v60
	s_waitcnt lgkmcnt(0)
	v_mfma_f32_16x16x32_bf16 v[52:55], v[56:59], v[4:7], v[52:55]
	v_add_u32_e32 v56, 0x100, v61
	v_cmp_gt_u32_e32 vcc, s22, v56
	v_cvt_f32_i32_e32 v56, v61
	s_and_b64 vcc, s[20:21], vcc
	v_mfma_f32_16x16x32_bf16 v[128:131], v[128:131], v[144:147], v[140:143]
	v_add_u32_e32 v68, s5, v180
	s_nop 1
	v_fma_f32 v52, |v56|, v153, v52
	v_add_u32_e32 v56, 0x104, v61
	v_mfma_f32_16x16x32_bf16 v[132:135], v[132:135], v[144:147], v[116:119]
	v_cndmask_b32_e32 v144, v234, v52, vcc
	v_add_u32_e32 v52, 4, v61
	v_cvt_f32_i32_e32 v52, v52
	v_cmp_gt_u32_e32 vcc, s22, v56
	s_and_b64 vcc, vcc, s[0:1]
	v_cmp_gt_u32_e64 s[0:1], s23, v60
	v_fma_f32 v52, |v52|, v153, v53
	v_cndmask_b32_e32 v145, v234, v52, vcc
	v_add_u32_e32 v52, 8, v61
	v_cvt_f32_i32_e32 v52, v52
	v_add_u32_e32 v53, 0x108, v61
	v_cmp_gt_u32_e32 vcc, s22, v53
	s_and_b64 vcc, vcc, s[0:1]
	v_fma_f32 v52, |v52|, v153, v54
	v_cndmask_b32_e32 v146, v234, v52, vcc
	v_add_u32_e32 v52, 12, v61
	v_cvt_f32_i32_e32 v52, v52
	v_add_u32_e32 v53, 0x10c, v61
	v_cmp_gt_u32_e32 vcc, s22, v53
	v_cmp_gt_u32_e64 s[0:1], s17, v60
	s_and_b64 vcc, vcc, s[0:1]
	v_fma_f32 v52, |v52|, v153, v55
	v_cndmask_b32_e32 v147, v234, v52, vcc
	ds_read_b128 v[52:55], v151 offset:11520
	ds_read_b128 v[56:59], v151 offset:11584
	s_waitcnt lgkmcnt(1)
	v_mfma_f32_16x16x32_bf16 v[52:55], v[52:55], v[8:11], v[12:15]
	v_cmp_gt_u32_e64 s[0:1], s58, v60
	v_med3_i32 v68, v68, 0, v233
	v_add_u32_e32 v76, s5, v181
	s_waitcnt lgkmcnt(0)
; #define A_LOAD(R, t_) do { int tb_, sd_, md_; a_desc((t_), a0, rho, tb_, sd_, md_); tile_load(R, kb, vb, tb_, sd_, lane); } while (0)
; #define A_STAGE(S, R, t_) do { int tb_, sd_, md_; a_desc((t_), a0, rho, tb_, sd_, md_); a_stage(S, R, vt, (t_) & 1, qf, cinit, tb_, sd_, md_, tq, nslope2, lane); } while (0)
; DI void mixerA2_unit(int u, const bf16* PROJ, bf16* YC, const float* LPA, const float* kmax_l, LAS char* vt, int wave, int lane) {
;     ...
;     A_STAGE(sB, R2, 5); A_LOAD(R2, 8);
;     fb_update(o, ol, sA[0], sA[1], vt, lane);
;     A_STAGE(sA, R0, 6); A_LOAD(R0, 9);
;     fb_update(o, ol, sB[0], sB[1], vt + A_V1, lane);
;     A_STAGE(sB, R1, 7);
;     fb_update(o, ol, sA[0], sA[1], vt, lane);
;     A_STAGE(sA, R2, 8);
	v_mfma_f32_16x16x32_bf16 v[52:55], v[56:59], v[4:7], v[52:55]
	v_add_u32_e32 v56, 64, v61
	v_cvt_f32_i32_e32 v56, v56
	v_add_u32_e32 v57, 0x140, v61
	v_cmp_gt_u32_e32 vcc, s22, v57
	s_and_b64 vcc, s[20:21], vcc
	s_nop 2
	v_fma_f32 v52, |v56|, v153, v52
	v_cndmask_b32_e32 v155, v234, v52, vcc
	v_add_u32_e32 v52, 0x44, v61
	v_cvt_f32_i32_e32 v52, v52
	v_add_u32_e32 v56, 0x144, v61
	v_cmp_gt_u32_e32 vcc, s22, v56
	s_and_b64 vcc, vcc, s[0:1]
	v_fma_f32 v52, |v52|, v153, v53
	v_cndmask_b32_e32 v186, v234, v52, vcc
	v_add_u32_e32 v52, 0x48, v61
	v_cvt_f32_i32_e32 v52, v52
	v_add_u32_e32 v53, 0x148, v61
	v_cmp_gt_u32_e32 vcc, s22, v53
	v_cmp_gt_u32_e64 s[0:1], s59, v60
	s_and_b64 vcc, vcc, s[0:1]
	v_fma_f32 v52, |v52|, v153, v54
	v_cndmask_b32_e32 v187, v234, v52, vcc
	v_add_u32_e32 v52, 0x4c, v61
	v_cvt_f32_i32_e32 v52, v52
	v_add_u32_e32 v53, 0x14c, v61
	v_cmp_gt_u32_e32 vcc, s22, v53
	v_cmp_gt_u32_e64 s[0:1], s52, v60
	s_and_b64 vcc, vcc, s[0:1]
	v_fma_f32 v52, |v52|, v153, v55
	v_cndmask_b32_e32 v191, v234, v52, vcc
	v_add_u32_e32 v52, s5, v178
	v_med3_i32 v52, v52, 0, v233
	v_add_u32_e32 v60, s5, v179
	v_lshlrev_b32_e32 v188, 7, v52
	v_med3_i32 v60, v60, 0, v233
	v_lshl_add_u64 v[52:53], v[156:157], 0, v[188:189]
	v_lshl_add_u64 v[56:57], v[158:159], 0, v[188:189]
	v_lshlrev_b32_e32 v188, 7, v60
	v_lshl_add_u64 v[60:61], v[156:157], 0, v[188:189]
	v_lshl_add_u64 v[64:65], v[158:159], 0, v[188:189]
	v_lshlrev_b32_e32 v188, 7, v68
	v_med3_i32 v76, v76, 0, v233
	v_lshl_add_u64 v[68:69], v[156:157], 0, v[188:189]
	v_lshl_add_u64 v[72:73], v[158:159], 0, v[188:189]
	v_lshlrev_b32_e32 v188, 7, v76
	v_lshl_add_u64 v[76:77], v[156:157], 0, v[188:189]
	v_exp_f32_e32 v116, v193
	v_exp_f32_e32 v117, v201
	v_exp_f32_e32 v118, v198
	v_exp_f32_e32 v119, v202
	v_exp_f32_e32 v141, v199
	v_exp_f32_e32 v143, v203
	v_exp_f32_e32 v142, v200
	v_exp_f32_e32 v156, v204
	v_lshl_add_u64 v[80:81], v[158:159], 0, v[188:189]
	v_cvt_pk_bf16_f32 v140, v116, v118
	v_cvt_pk_bf16_f32 v141, v141, v142
	v_cvt_pk_bf16_f32 v142, v117, v119
	v_cvt_pk_bf16_f32 v143, v143, v156
	global_load_dwordx4 v[52:55], v[52:53], off
	s_nop 0
	global_load_dwordx4 v[56:59], v[56:57], off
	v_mfma_f32_16x16x32_bf16 v[116:119], v[16:19], v[140:143], v[136:139]
	global_load_dwordx4 v[60:63], v[60:61], off
	s_nop 0
	global_load_dwordx4 v[64:67], v[64:65], off
	s_nop 0
	global_load_dwordx4 v[68:71], v[68:69], off
	s_nop 0
	global_load_dwordx4 v[72:75], v[72:73], off
	s_nop 0
	global_load_dwordx4 v[76:79], v[76:77], off
	s_nop 0
	global_load_dwordx4 v[80:83], v[80:81], off
	ds_read_b64_tr_b16 v[138:139], v184 offset:6912
	ds_read_b64_tr_b16 v[136:137], v184 offset:4608
	ds_read_b64_tr_b16 v[156:157], v184 offset:4640
	ds_read_b64_tr_b16 v[158:159], v184 offset:6944
	s_waitcnt lgkmcnt(2)
	v_mfma_f32_16x16x32_bf16 v[136:139], v[136:139], v[140:143], v[120:123]
	s_waitcnt lgkmcnt(0)
	v_mfma_f32_16x16x32_bf16 v[120:123], v[156:159], v[140:143], v[124:127]
	s_nop 2
	ds_read_b64_tr_b16 v[124:125], v184 offset:4672
	ds_read_b64_tr_b16 v[126:127], v184 offset:6976
	s_waitcnt lgkmcnt(0)
	v_mfma_f32_16x16x32_bf16 v[124:127], v[124:127], v[140:143], v[128:131]
	s_nop 2
	ds_read_b64_tr_b16 v[128:129], v184 offset:4704
	ds_read_b64_tr_b16 v[130:131], v184 offset:7008
	s_waitcnt vmcnt(22)
	ds_write_b128 v183, v[112:115] offset:4608
	ds_write_b128 v183, v[108:111] offset:9216
	s_waitcnt vmcnt(20)
	ds_write_b128 v183, v[104:107] offset:5760
	ds_write_b128 v183, v[100:103] offset:10368
	s_waitcnt vmcnt(18)
	ds_write_b128 v183, v[96:99] offset:6912
	ds_write_b128 v183, v[92:95] offset:11520
	s_waitcnt vmcnt(16)
	ds_write_b128 v183, v[88:91] offset:8064
	ds_write_b128 v183, v[84:87] offset:12672
	ds_read_b128 v[84:87], v151 offset:9216
	ds_read_b128 v[88:91], v151 offset:9280
	s_waitcnt lgkmcnt(1)
	v_mfma_f32_16x16x32_bf16 v[84:87], v[84:87], v[8:11], v[12:15]
	v_or_b32_e32 v99, s16, v168
	v_sub_u32_e32 v100, v99, v154
	v_cmp_gt_u32_e64 s[0:1], s67, v99
	s_waitcnt lgkmcnt(0)
	v_mfma_f32_16x16x32_bf16 v[84:87], v[88:91], v[4:7], v[84:87]
	v_add_u32_e32 v88, 0x100, v100
	v_cmp_gt_u32_e32 vcc, s22, v88
	v_cvt_f32_i32_e32 v88, v100
	s_and_b64 vcc, s[20:21], vcc
	v_mfma_f32_16x16x32_bf16 v[128:131], v[128:131], v[140:143], v[132:135]
	s_nop 2
	v_fma_f32 v84, |v88|, v153, v84
	v_cndmask_b32_e32 v92, v234, v84, vcc
	v_add_u32_e32 v84, 4, v100
	v_cvt_f32_i32_e32 v84, v84
	v_add_u32_e32 v88, 0x104, v100
	v_cmp_gt_u32_e32 vcc, s22, v88
	s_and_b64 vcc, vcc, s[0:1]
	v_fma_f32 v84, |v84|, v153, v85
	v_cndmask_b32_e32 v93, v234, v84, vcc
	v_add_u32_e32 v84, 8, v100
	v_cvt_f32_i32_e32 v84, v84
	v_add_u32_e32 v85, 0x108, v100
	v_cmp_gt_u32_e32 vcc, s22, v85
	v_cmp_gt_u32_e64 s[0:1], s23, v99
	s_and_b64 vcc, vcc, s[0:1]
	v_fma_f32 v84, |v84|, v153, v86
	v_cndmask_b32_e32 v94, v234, v84, vcc
	v_add_u32_e32 v84, 12, v100
	v_cvt_f32_i32_e32 v84, v84
	v_add_u32_e32 v85, 0x10c, v100
	v_cmp_gt_u32_e32 vcc, s22, v85
	v_cmp_gt_u32_e64 s[0:1], s17, v99
	s_and_b64 vcc, vcc, s[0:1]
	v_fma_f32 v84, |v84|, v153, v87
	v_cndmask_b32_e32 v95, v234, v84, vcc
	ds_read_b128 v[84:87], v151 offset:11520
	ds_read_b128 v[88:91], v151 offset:11584
	s_waitcnt lgkmcnt(1)
	v_mfma_f32_16x16x32_bf16 v[84:87], v[84:87], v[8:11], v[12:15]
	s_waitcnt lgkmcnt(0)
; DI void fb_update(f32x4 (&o)[4], f32x4& ol, const f32x4 st0, const f32x4 st1, const LAS char* vt, int lane) {
;     f32x4 p0, p1;
; #pragma unroll
;     for (int i = 0; i < 4; ++i) { p0[i] = ex2(st0[i]); p1[i] = ex2(st1[i]); }
;     const bf16x8 pf = pack8(p0, p1);
;     const bf16x8 ones = {0x3F80, 0x3F80, 0x3F80, 0x3F80, 0x3F80, 0x3F80, 0x3F80, 0x3F80};
;     ol = MFMA16(ones, pf, ol);
;     const int g = lane >> 4, q = (lane & 15) >> 2, p = lane & 3;
;     const LAS char* v0 = vt + (4 * g + q) * VT_PITCH + 8 * p;
;     const LAS char* v1 = v0 + 16 * VT_PITCH;
; #pragma unroll
;     for (int c = 0; c < 4; ++c) { const bf16x8 vf = cat8(vtr(v0 + 32 * c), vtr(v1 + 32 * c)); o[c] = MFMA16(vf, pf, o[c]); }
; }
; DI float q_norm2(const bf16x8 (&qf)[2]) { float a = sumsq8(qf[0]) + sumsq8(qf[1]); a += __shfl_xor(a, 16); a += __shfl_xor(a, 32); return a; }
; DI void a_desc(int ti, int a0, int rho, int& tokbase, int& stride, int& maxd) {
;     if (ti < 4) { stride = 16; tokbase = rho + 512 * ti; maxd = 1024; }
;     else if (ti < 10) { stride = 4; const int m0 = 4 * a0 + (rho >> 2) - 64 + 32 * (ti - 4); tokbase = 4 * m0 + (rho & 3); maxd = 256; }
;     else { stride = 1; tokbase = 16 * a0 + rho - 64 + 32 * (ti - 10); maxd = 64; }
; }
; template <bool EDGE>
; DI void a_scores(f32x4 (&st)[2], const LAS char* kt, const bf16x8 (&qf)[2], const f32x4 cinit, int tokbase, int stride, int maxd, int tq, float nslope2, int lane) {
;     const int g = lane >> 4;
;     const int base0 = tokbase + stride * 4 * g - tq;
; #pragma unroll
;     for (int t = 0; t < 2; ++t) {
;         st[t] = MFMA16(k_frag_at(kt, t, 0, lane), qf[0], cinit); st[t] = MFMA16(k_frag_at(kt, t, 1, lane), qf[1], st[t]);
; #pragma unroll
;         for (int i = 0; i < 4; ++i) { const int d = base0 + stride * (16 * t + i);
;             bool ok = (unsigned)(d + maxd) <= (unsigned)(2 * maxd);
;             if (EDGE) ok = ok && ((unsigned)(d + tq) < (unsigned)T);
;             const float v = __builtin_fmaf(__builtin_fabsf((float)d), nslope2, st[t][i]);
;             st[t][i] = ok ? v : -1e30f; }
;     }
; }
; DI void a_stage(f32x4 (&st)[2], const TileRegs& R, LAS char* vt, int vpar, const bf16x8 (&qf)[2], const f32x4 cinit, int tokbase, int stride, int maxd, int tq, float nslope2, int lane) {
; #pragma unroll
;     for (int it = 0; it < 4; ++it) { const int n = lane + 64 * it, row = n >> 3, ch = n & 7;
	v_mfma_f32_16x16x32_bf16 v[84:87], v[88:91], v[4:7], v[84:87]
	v_add_u32_e32 v88, 64, v100
	v_cvt_f32_i32_e32 v88, v88
	v_add_u32_e32 v89, 0x140, v100
	v_cmp_gt_u32_e32 vcc, s22, v89
	s_and_b64 vcc, s[20:21], vcc
	s_nop 2
	v_fma_f32 v84, |v88|, v153, v84
	v_cndmask_b32_e32 v96, v234, v84, vcc
	v_add_u32_e32 v84, 0x44, v100
	v_cvt_f32_i32_e32 v84, v84
	v_add_u32_e32 v88, 0x144, v100
	v_cmp_gt_u32_e32 vcc, s22, v88
	v_add_u32_e32 v88, 0x44, v99
	v_cmp_gt_u32_e64 s[0:1], s24, v88
	s_and_b64 vcc, vcc, s[0:1]
	v_fma_f32 v84, |v84|, v153, v85
	v_cndmask_b32_e32 v97, v234, v84, vcc
	v_add_u32_e32 v84, 0x48, v100
	v_cvt_f32_i32_e32 v84, v84
	v_add_u32_e32 v85, 0x148, v100
	v_cmp_gt_u32_e32 vcc, s22, v85
	v_add_u32_e32 v85, 0x48, v99
	v_cmp_gt_u32_e64 s[0:1], s24, v85
	s_and_b64 vcc, vcc, s[0:1]
	v_fma_f32 v84, |v84|, v153, v86
	v_cndmask_b32_e32 v98, v234, v84, vcc
	v_add_u32_e32 v84, 0x4c, v100
	v_add_u32_e32 v85, 0x14c, v100
	v_exp_f32_e32 v91, v187
	v_exp_f32_e32 v100, v191
	v_cvt_f32_i32_e32 v84, v84
	v_cmp_gt_u32_e32 vcc, s22, v85
	v_add_u32_e32 v85, 0x4c, v99
	v_cvt_pk_bf16_f32 v91, v91, v100
	ds_read_b64_tr_b16 v[102:103], v184 offset:2304
	ds_read_b64_tr_b16 v[100:101], v184
	ds_read_b64_tr_b16 v[104:105], v184 offset:32
	ds_read_b64_tr_b16 v[106:107], v184 offset:2336
	ds_read_b64_tr_b16 v[108:109], v184 offset:64
	ds_read_b64_tr_b16 v[110:111], v184 offset:2368
	ds_read_b64_tr_b16 v[112:113], v184 offset:96
	ds_read_b64_tr_b16 v[114:115], v184 offset:2400
	s_waitcnt vmcnt(14)
	ds_write_b128 v183, v[48:51]
	ds_write_b128 v183, v[44:47] offset:9216
	s_waitcnt vmcnt(12)
	ds_write_b128 v183, v[36:39] offset:1152
	ds_write_b128 v183, v[20:23] offset:10368
	s_waitcnt vmcnt(10)
	ds_write_b128 v183, v[28:31] offset:2304
	ds_write_b128 v183, v[24:27] offset:11520
	s_waitcnt vmcnt(8)
	ds_write_b128 v183, v[40:43] offset:3456
	ds_write_b128 v183, v[32:35] offset:12672
	ds_read_b128 v[20:23], v151 offset:9216
	ds_read_b128 v[24:27], v151 offset:9280
	s_waitcnt lgkmcnt(1)
	v_mfma_f32_16x16x32_bf16 v[20:23], v[20:23], v[8:11], v[12:15]
	v_or_b32_e32 v28, s33, v168
	v_cmp_gt_u32_e64 s[0:1], s24, v85
	v_sub_u32_e32 v29, v28, v154
	s_and_b64 vcc, vcc, s[0:1]
	v_fma_f32 v84, |v84|, v153, v87
	s_waitcnt lgkmcnt(0)
	v_mfma_f32_16x16x32_bf16 v[20:23], v[24:27], v[4:7], v[20:23]
	v_add_u32_e32 v24, 0x100, v29
	v_cndmask_b32_e32 v99, v234, v84, vcc
	v_cmp_gt_u32_e32 vcc, s22, v24
	v_cvt_f32_i32_e32 v24, v29
	s_and_b64 vcc, s[96:97], vcc
	v_cmp_gt_u32_e64 s[0:1], s67, v28
	v_exp_f32_e32 v84, v144
	s_nop 0
	v_fma_f32 v20, |v24|, v153, v20
	v_cndmask_b32_e32 v48, v234, v20, vcc
	v_add_u32_e32 v20, 4, v29
	v_cvt_f32_i32_e32 v20, v20
	v_add_u32_e32 v24, 0x104, v29
	v_cmp_gt_u32_e32 vcc, s22, v24
	s_and_b64 vcc, vcc, s[0:1]
	v_fma_f32 v20, |v20|, v153, v21
	v_cndmask_b32_e32 v49, v234, v20, vcc
	v_add_u32_e32 v20, 8, v29
	v_cvt_f32_i32_e32 v20, v20
	v_add_u32_e32 v21, 0x108, v29
	v_cmp_gt_u32_e32 vcc, s22, v21
	v_cmp_gt_u32_e64 s[0:1], s23, v28
	s_and_b64 vcc, vcc, s[0:1]
	v_fma_f32 v20, |v20|, v153, v22
	v_cndmask_b32_e32 v50, v234, v20, vcc
	v_add_u32_e32 v20, 12, v29
	v_cvt_f32_i32_e32 v20, v20
	v_add_u32_e32 v21, 0x10c, v29
	v_cmp_gt_u32_e32 vcc, s22, v21
	v_cmp_gt_u32_e64 s[0:1], s17, v28
	s_and_b64 vcc, vcc, s[0:1]
	v_fma_f32 v20, |v20|, v153, v23
	v_cndmask_b32_e32 v51, v234, v20, vcc
	ds_read_b128 v[20:23], v151 offset:11520
	ds_read_b128 v[24:27], v151 offset:11584
	s_waitcnt lgkmcnt(1)
	v_mfma_f32_16x16x32_bf16 v[20:23], v[20:23], v[8:11], v[12:15]
	v_exp_f32_e32 v85, v155
	v_exp_f32_e32 v86, v145
	v_exp_f32_e32 v87, v186
	s_waitcnt lgkmcnt(0)
	v_mfma_f32_16x16x32_bf16 v[20:23], v[24:27], v[4:7], v[20:23]
	v_add_u32_e32 v24, 64, v29
	v_exp_f32_e32 v89, v146
	v_exp_f32_e32 v90, v147
	v_cvt_f32_i32_e32 v24, v24
	v_add_u32_e32 v25, 0x140, v29
	v_cmp_gt_u32_e32 vcc, s22, v25
	v_cvt_pk_bf16_f32 v88, v84, v86
	v_cvt_pk_bf16_f32 v89, v89, v90
	v_cvt_pk_bf16_f32 v90, v85, v87
	s_and_b64 vcc, s[96:97], vcc
	v_fma_f32 v20, |v24|, v153, v20
	v_mfma_f32_16x16x32_bf16 v[84:87], v[16:19], v[88:91], v[116:119]
	v_add_u32_e32 v24, 0x144, v29
	v_cmp_gt_u32_e64 s[0:1], s58, v28
	v_exp_f32_e32 v25, v98
	v_mfma_f32_16x16x32_bf16 v[100:103], v[100:103], v[88:91], v[136:139]
	v_exp_f32_e32 v26, v95
	v_exp_f32_e32 v27, v99
	v_mfma_f32_16x16x32_bf16 v[104:107], v[104:107], v[88:91], v[120:123]
	v_mfma_f32_16x16x32_bf16 v[108:111], v[108:111], v[88:91], v[124:127]
	v_mfma_f32_16x16x32_bf16 v[88:91], v[112:115], v[88:91], v[128:131]
	v_cndmask_b32_e32 v112, v234, v20, vcc
	v_add_u32_e32 v20, 0x44, v29
	v_cvt_f32_i32_e32 v20, v20
	v_cmp_gt_u32_e32 vcc, s22, v24
	s_and_b64 vcc, vcc, s[0:1]
	v_cmp_gt_u32_e64 s[0:1], s59, v28
	v_fma_f32 v20, |v20|, v153, v21
	v_cndmask_b32_e32 v113, v234, v20, vcc
	v_add_u32_e32 v20, 0x48, v29
	v_cvt_f32_i32_e32 v20, v20
	v_add_u32_e32 v21, 0x148, v29
	v_cmp_gt_u32_e32 vcc, s22, v21
	s_and_b64 vcc, vcc, s[0:1]
	v_fma_f32 v20, |v20|, v153, v22
	v_cndmask_b32_e32 v114, v234, v20, vcc
	v_add_u32_e32 v20, 0x4c, v29
	v_cvt_f32_i32_e32 v20, v20
	v_add_u32_e32 v21, 0x14c, v29
	v_cmp_gt_u32_e64 s[0:1], s52, v28
	ds_read_b64_tr_b16 v[30:31], v184 offset:6912
	ds_read_b64_tr_b16 v[28:29], v184 offset:4608
	ds_read_b64_tr_b16 v[32:33], v184 offset:4640
	ds_read_b64_tr_b16 v[34:35], v184 offset:6944
	v_cmp_gt_u32_e32 vcc, s22, v21
	s_and_b64 vcc, vcc, s[0:1]
	v_fma_f32 v20, |v20|, v153, v23
	v_cndmask_b32_e32 v115, v234, v20, vcc
	v_exp_f32_e32 v20, v92
	v_exp_f32_e32 v22, v96
	v_exp_f32_e32 v21, v93
	v_exp_f32_e32 v23, v97
	v_exp_f32_e32 v24, v94
	ds_read_b64_tr_b16 v[36:37], v184 offset:4672
	ds_read_b64_tr_b16 v[38:39], v184 offset:6976
	ds_read_b64_tr_b16 v[40:41], v184 offset:4704
	ds_read_b64_tr_b16 v[42:43], v184 offset:7008
	v_cvt_pk_bf16_f32 v20, v20, v21
	v_cvt_pk_bf16_f32 v21, v24, v26
	v_cvt_pk_bf16_f32 v22, v22, v23
	v_cvt_pk_bf16_f32 v23, v25, v27
	s_waitcnt vmcnt(6)
; DI void fb_update(f32x4 (&o)[4], f32x4& ol, const f32x4 st0, const f32x4 st1, const LAS char* vt, int lane) {
;     f32x4 p0, p1;
; #pragma unroll
;     for (int i = 0; i < 4; ++i) { p0[i] = ex2(st0[i]); p1[i] = ex2(st1[i]); }
;     const bf16x8 pf = pack8(p0, p1);
;     const bf16x8 ones = {0x3F80, 0x3F80, 0x3F80, 0x3F80, 0x3F80, 0x3F80, 0x3F80, 0x3F80};
;     ol = MFMA16(ones, pf, ol);
;     const int g = lane >> 4, q = (lane & 15) >> 2, p = lane & 3;
;     const LAS char* v0 = vt + (4 * g + q) * VT_PITCH + 8 * p;
;     const LAS char* v1 = v0 + 16 * VT_PITCH;
; #pragma unroll
;     for (int c = 0; c < 4; ++c) { const bf16x8 vf = cat8(vtr(v0 + 32 * c), vtr(v1 + 32 * c)); o[c] = MFMA16(vf, pf, o[c]); }
; }
; DI float q_norm2(const bf16x8 (&qf)[2]) { float a = sumsq8(qf[0]) + sumsq8(qf[1]); a += __shfl_xor(a, 16); a += __shfl_xor(a, 32); return a; }
; DI void a_desc(int ti, int a0, int rho, int& tokbase, int& stride, int& maxd) {
;     if (ti < 4) { stride = 16; tokbase = rho + 512 * ti; maxd = 1024; }
;     else if (ti < 10) { stride = 4; const int m0 = 4 * a0 + (rho >> 2) - 64 + 32 * (ti - 4); tokbase = 4 * m0 + (rho & 3); maxd = 256; }
;     else { stride = 1; tokbase = 16 * a0 + rho - 64 + 32 * (ti - 10); maxd = 64; }
; }
; template <bool EDGE>
; DI void a_scores(f32x4 (&st)[2], const LAS char* kt, const bf16x8 (&qf)[2], const f32x4 cinit, int tokbase, int stride, int maxd, int tq, float nslope2, int lane) {
;     const int g = lane >> 4;
;     const int base0 = tokbase + stride * 4 * g - tq;
; #pragma unroll
;     for (int t = 0; t < 2; ++t) {
;         st[t] = MFMA16(k_frag_at(kt, t, 0, lane), qf[0], cinit); st[t] = MFMA16(k_frag_at(kt, t, 1, lane), qf[1], st[t]);
; #pragma unroll
;         for (int i = 0; i < 4; ++i) { const int d = base0 + stride * (16 * t + i);
;             bool ok = (unsigned)(d + maxd) <= (unsigned)(2 * maxd);
;             if (EDGE) ok = ok && ((unsigned)(d + tq) < (unsigned)T);
;             const float v = __builtin_fmaf(__builtin_fabsf((float)d), nslope2, st[t][i]);
;             st[t][i] = ok ? v : -1e30f; }
;     }
; }
; DI void a_stage(f32x4 (&st)[2], const TileRegs& R, LAS char* vt, int vpar, const bf16x8 (&qf)[2], const f32x4 cinit, int tokbase, int stride, int maxd, int tq, float nslope2, int lane) {
; #pragma unroll
;     for (int it = 0; it < 4; ++it) { const int n = lane + 64 * it, row = n >> 3, ch = n & 7;
	ds_write_b128 v183, v[56:59] offset:4608
	ds_write_b128 v183, v[52:55] offset:9216
	s_waitcnt vmcnt(4)
	ds_write_b128 v183, v[64:67] offset:5760
	ds_write_b128 v183, v[60:63] offset:10368
	s_waitcnt vmcnt(2)
	ds_write_b128 v183, v[72:75] offset:6912
	ds_write_b128 v183, v[68:71] offset:11520
	s_waitcnt vmcnt(0)
	ds_write_b128 v183, v[80:83] offset:8064
	ds_write_b128 v183, v[76:79] offset:12672
	v_mfma_f32_16x16x32_bf16 v[24:27], v[16:19], v[20:23], v[84:87]
	ds_read_b128 v[44:47], v151 offset:9280
	v_or_b32_e32 v52, s5, v168
	v_sub_u32_e32 v53, v52, v154
	s_waitcnt lgkmcnt(14)
	v_mfma_f32_16x16x32_bf16 v[28:31], v[28:31], v[20:23], v[100:103]
	v_cmp_gt_u32_e64 s[0:1], s67, v52
	s_waitcnt lgkmcnt(13)
	v_mfma_f32_16x16x32_bf16 v[32:35], v[32:35], v[20:23], v[104:107]
	s_waitcnt lgkmcnt(11)
	v_mfma_f32_16x16x32_bf16 v[36:39], v[36:39], v[20:23], v[108:111]
	s_waitcnt lgkmcnt(9)
	v_mfma_f32_16x16x32_bf16 v[20:23], v[40:43], v[20:23], v[88:91]
	ds_read_b128 v[40:43], v151 offset:9216
	s_waitcnt lgkmcnt(0)
	v_mfma_f32_16x16x32_bf16 v[40:43], v[40:43], v[8:11], v[12:15]
	v_mfma_f32_16x16x32_bf16 v[40:43], v[44:47], v[4:7], v[40:43]
	v_add_u32_e32 v44, 0x100, v53
	v_cmp_gt_u32_e32 vcc, s22, v44
	v_cvt_f32_i32_e32 v44, v53
	s_and_b64 vcc, s[26:27], vcc
	v_add_u32_e32 v45, 0x104, v53
	s_nop 2
	v_fma_f32 v40, |v44|, v153, v40
	v_cndmask_b32_e32 v44, v234, v40, vcc
	v_add_u32_e32 v40, 4, v53
	v_cvt_f32_i32_e32 v40, v40
	v_cmp_gt_u32_e32 vcc, s22, v45
	s_and_b64 vcc, vcc, s[0:1]
	v_cmp_gt_u32_e64 s[0:1], s23, v52
	v_fma_f32 v40, |v40|, v153, v41
	v_cndmask_b32_e32 v45, v234, v40, vcc
	v_add_u32_e32 v40, 8, v53
	v_cvt_f32_i32_e32 v40, v40
	v_add_u32_e32 v41, 0x108, v53
	v_cmp_gt_u32_e32 vcc, s22, v41
	s_and_b64 vcc, vcc, s[0:1]
	v_fma_f32 v40, |v40|, v153, v42
	v_cndmask_b32_e32 v46, v234, v40, vcc
	v_add_u32_e32 v40, 12, v53
	v_cvt_f32_i32_e32 v40, v40
	v_add_u32_e32 v41, 0x10c, v53
	v_cmp_gt_u32_e32 vcc, s22, v41
	v_cmp_gt_u32_e64 s[0:1], s17, v52
	s_and_b64 vcc, vcc, s[0:1]
	v_fma_f32 v40, |v40|, v153, v43
	v_cndmask_b32_e32 v47, v234, v40, vcc
	ds_read_b128 v[40:43], v151 offset:11520
	s_waitcnt lgkmcnt(0)
	v_mfma_f32_16x16x32_bf16 v[8:11], v[40:43], v[8:11], v[12:15]
	s_nop 2
	ds_read_b128 v[12:15], v151 offset:11584
	s_waitcnt lgkmcnt(0)
	v_mfma_f32_16x16x32_bf16 v[4:7], v[12:15], v[4:7], v[8:11]
	s_nop 2
	v_add_u32_e32 v8, 64, v53
	v_cvt_f32_i32_e32 v8, v8
	v_add_u32_e32 v9, 0x140, v53
	v_cmp_gt_u32_e32 vcc, s22, v9
	s_and_b64 vcc, s[26:27], vcc
	v_fma_f32 v4, |v8|, v153, v4
	v_cndmask_b32_e32 v40, v234, v4, vcc
	v_add_u32_e32 v4, 0x44, v53
	v_cvt_f32_i32_e32 v4, v4
	v_add_u32_e32 v8, 0x144, v53
	v_cmp_gt_u32_e32 vcc, s22, v8
	v_add_u32_e32 v8, 0x44, v52
	v_cmp_gt_u32_e64 s[0:1], s24, v8
	s_and_b64 vcc, vcc, s[0:1]
	v_fma_f32 v4, |v4|, v153, v5
	v_cndmask_b32_e32 v41, v234, v4, vcc
	v_add_u32_e32 v4, 0x48, v53
	v_cvt_f32_i32_e32 v4, v4
	v_add_u32_e32 v5, 0x148, v53
	v_cmp_gt_u32_e32 vcc, s22, v5
	v_add_u32_e32 v5, 0x48, v52
	v_cmp_gt_u32_e64 s[0:1], s24, v5
	s_and_b64 vcc, vcc, s[0:1]
	v_fma_f32 v4, |v4|, v153, v6
	v_cndmask_b32_e32 v42, v234, v4, vcc
	v_add_u32_e32 v4, 0x4c, v53
	v_cvt_f32_i32_e32 v4, v4
	v_add_u32_e32 v5, 0x14c, v53
	v_cmp_gt_u32_e32 vcc, s22, v5
	v_add_u32_e32 v5, 0x4c, v52
	v_cmp_gt_u32_e64 s[0:1], s24, v5
	s_and_b64 vcc, vcc, s[0:1]
	v_fma_f32 v4, |v4|, v153, v7
	v_cndmask_b32_e32 v43, v234, v4, vcc
	v_exp_f32_e32 v4, v48
	v_exp_f32_e32 v6, v112
	v_exp_f32_e32 v5, v49
	v_exp_f32_e32 v7, v113
	v_exp_f32_e32 v8, v50
	v_exp_f32_e32 v9, v114
	v_exp_f32_e32 v10, v51
	v_exp_f32_e32 v11, v115
	v_cvt_pk_bf16_f32 v4, v4, v5
	v_cvt_pk_bf16_f32 v6, v6, v7
	v_cvt_pk_bf16_f32 v5, v8, v10
	v_cvt_pk_bf16_f32 v7, v9, v11
	s_lshl_b64 s[0:1], s[94:95], 22
	s_add_u32 s0, s8, s0
	v_mfma_f32_16x16x32_bf16 v[8:11], v[16:19], v[4:7], v[24:27]
	ds_read_b64_tr_b16 v[14:15], v184 offset:2304
	ds_read_b64_tr_b16 v[12:13], v184
	s_nop 0
	ds_read_b64_tr_b16 v[24:25], v184 offset:32
	ds_read_b64_tr_b16 v[26:27], v184 offset:2336
	s_addc_u32 s1, s9, s1
	s_waitcnt lgkmcnt(2)
	v_mfma_f32_16x16x32_bf16 v[12:15], v[12:15], v[4:7], v[28:31]
	s_nop 2
	ds_read_b64_tr_b16 v[28:29], v184 offset:64
	ds_read_b64_tr_b16 v[30:31], v184 offset:2368
	s_lshl_b32 s2, s2, 7
	s_add_u32 s0, s0, s2
	s_waitcnt lgkmcnt(2)
	v_mfma_f32_16x16x32_bf16 v[24:27], v[24:27], v[4:7], v[32:35]
	s_nop 2
	ds_read_b64_tr_b16 v[32:33], v184 offset:96
	ds_read_b64_tr_b16 v[34:35], v184 offset:2400
	s_addc_u32 s1, s1, 0
	v_mov_b32_e32 v153, v189
	s_waitcnt lgkmcnt(2)
	v_mfma_f32_16x16x32_bf16 v[28:31], v[28:31], v[4:7], v[36:39]
	s_add_i32 s69, s69, 4
	s_bitcmp1_b32 s69, 2
	s_waitcnt lgkmcnt(0)
	v_mfma_f32_16x16x32_bf16 v[4:7], v[32:35], v[4:7], v[20:23]
	v_exp_f32_e32 v32, v46
	v_exp_f32_e32 v33, v42
	v_exp_f32_e32 v34, v47
	v_exp_f32_e32 v20, v44
	v_exp_f32_e32 v22, v40
	v_exp_f32_e32 v21, v45
	v_exp_f32_e32 v23, v41
	v_exp_f32_e32 v35, v43
	v_or_b32_e32 v40, s4, v163
	v_cvt_pk_bf16_f32 v20, v20, v21
	v_cvt_pk_bf16_f32 v21, v32, v34
	v_cvt_pk_bf16_f32 v22, v22, v23
	v_cvt_pk_bf16_f32 v23, v33, v35
	v_ashrrev_i32_e32 v41, 31, v40
	s_nop 0
	v_mfma_f32_16x16x32_bf16 v[32:35], v[16:19], v[20:23], v[8:11]
	s_nop 2
	ds_read_b64_tr_b16 v[8:9], v184 offset:4608
	ds_read_b64_tr_b16 v[10:11], v184 offset:6912
	s_nop 2
	v_add_u32_e32 v34, v169, v148
	s_waitcnt lgkmcnt(0)
	v_mfma_f32_16x16x32_bf16 v[16:19], v[8:11], v[20:23], v[12:15]
	ds_read_b64_tr_b16 v[8:9], v184 offset:4640
	ds_read_b64_tr_b16 v[10:11], v184 offset:6944
	s_waitcnt lgkmcnt(0)
	v_mfma_f32_16x16x32_bf16 v[12:15], v[8:11], v[20:23], v[24:27]
	ds_read_b64_tr_b16 v[8:9], v184 offset:4672
	ds_read_b64_tr_b16 v[10:11], v184 offset:6976
	s_nop 0
	ds_read_b64_tr_b16 v[24:25], v184 offset:4704
	ds_read_b64_tr_b16 v[26:27], v184 offset:7008
	s_waitcnt lgkmcnt(2)
; #define LAS __attribute__((address_space(3)))
; DI unsigned pk2(float lo, float hi) { f32x2_t v = {lo, hi}; bf16x2_t b = __builtin_convertvector(v, bf16x2_t); return __builtin_bit_cast(unsigned, b); }
; DI float silu_f(float x) { return x * __builtin_amdgcn_rcpf(1.f + __expf(-x)); }
; DI void mixerA2_unit(int u, const bf16* PROJ, bf16* YC, const float* LPA, const float* kmax_l, LAS char* vt, int wave, int lane) {
;     ...
;     const float inv = 1.f / (ol[0] + LPA[(size_t)(b * T + tq) * 4 + h]);
;     LAS char* sc = vt + SC_OFF; const int tok0 = 16 * a0 + rho;
;     bf16* ybase = YC + (size_t)b * T * 1024 + h * 64;
;     u32x2 pv[4], gv[4];
;     rows16_load(sc, ybase, 1024, tok0, 16, lane);
; #pragma unroll
;     for (int c = 0; c < 4; ++c) pv[c] = *(const LAS u32x2*)(sc + r * VT_PITCH + (16 * c + 4 * g) * 2);
;     rows16_load(sc, slab(PROJ, C_AG + h * 64, b), 64, tok0, 16, lane);
; #pragma unroll
;     for (int c = 0; c < 4; ++c) gv[c] = *(const LAS u32x2*)(sc + r * VT_PITCH + (16 * c + 4 * g) * 2);
; #pragma unroll
;     for (int c = 0; c < 4; ++c) {
;         f32x4 ov = o[c]; ov[0] += bflo(pv[c].x); ov[1] += bfhi(pv[c].x); ov[2] += bflo(pv[c].y); ov[3] += bfhi(pv[c].y); ov = ov * inv;
;         u32x2 w; w.x = pk2(ov[0] * silu_f(bflo(gv[c].x)), ov[1] * silu_f(bfhi(gv[c].x))); w.y = pk2(ov[2] * silu_f(bflo(gv[c].y)), ov[3] * silu_f(bfhi(gv[c].y)));
;         *(LAS u32x2*)(sc + r * VT_PITCH + (16 * c + 4 * g) * 2) = w; }
	v_mfma_f32_16x16x32_bf16 v[8:11], v[8:11], v[20:23], v[28:31]
	s_nop 2
	v_add_u32_e32 v29, v182, v166
	s_waitcnt lgkmcnt(0)
	v_mfma_f32_16x16x32_bf16 v[4:7], v[24:27], v[20:23], v[4:7]
	v_lshl_add_u32 v20, s94, 11, v154
	v_ashrrev_i32_e32 v21, 31, v20
	v_lshl_add_u64 v[20:21], v[20:21], 4, s[56:57]
	v_lshl_add_u64 v[20:21], v[20:21], 0, s[34:35]
	global_load_dword v20, v[20:21], off
	v_lshl_add_u64 v[26:27], s[0:1], 0, v[152:153]
	s_mov_b64 s[0:1], 0x1800000
	s_waitcnt vmcnt(0)
	v_add_f32_e32 v28, v32, v20
	v_or_b32_e32 v32, s4, v162
	v_ashrrev_i32_e32 v33, 31, v32
	v_lshlrev_b64 v[20:21], 11, v[32:33]
	v_lshl_add_u64 v[20:21], v[26:27], 0, v[20:21]
	global_load_dwordx4 v[22:25], v[20:21], off
	v_lshlrev_b64 v[32:33], 7, v[32:33]
	s_waitcnt vmcnt(0)
	ds_write_b128 v29, v[22:25] offset:9216
	v_lshlrev_b64 v[22:23], 11, v[40:41]
	v_lshl_add_u64 v[22:23], v[26:27], 0, v[22:23]
	global_load_dwordx4 v[24:27], v[22:23], off
	s_waitcnt vmcnt(0)
	ds_write_b128 v185, v[24:27] offset:9216
	v_lshl_add_u64 v[24:25], s[30:31], 0, v[152:153]
	v_lshl_add_u64 v[24:25], v[24:25], 0, s[0:1]
	v_lshl_add_u64 v[32:33], v[24:25], 0, v[32:33]
	ds_read_b64 v[42:43], v34 offset:9216
	ds_read_b64 v[44:45], v34 offset:9248
	ds_read_b64 v[30:31], v34 offset:9280
	ds_read_b64 v[26:27], v34 offset:9312
	global_load_dwordx4 v[36:39], v[32:33], off
	v_lshlrev_b64 v[32:33], 7, v[40:41]
	v_lshl_add_u64 v[24:25], v[24:25], 0, v[32:33]
	v_div_scale_f32 v35, s[0:1], v28, v28, 1.0
	v_rcp_f32_e32 v40, v35
	s_waitcnt vmcnt(0)
	ds_write_b128 v29, v[36:39] offset:9216
	global_load_dwordx4 v[36:39], v[24:25], off
	v_fma_f32 v41, -v35, v40, 1.0
	v_fmac_f32_e32 v40, v41, v40
	v_div_scale_f32 v41, vcc, 1.0, v28, 1.0
	v_mul_f32_e32 v46, v41, v40
	v_fma_f32 v47, -v35, v46, v41
	v_fmac_f32_e32 v46, v47, v40
	v_fma_f32 v35, -v35, v46, v41
	v_div_fmas_f32 v35, v35, v40, v46
	s_waitcnt lgkmcnt(4)
	v_lshlrev_b32_e32 v40, 16, v42
	v_and_b32_e32 v41, 0xffff0000, v42
	v_pk_add_f32 v[16:17], v[16:17], v[40:41]
	v_lshlrev_b32_e32 v40, 16, v43
	v_and_b32_e32 v41, 0xffff0000, v43
	v_pk_add_f32 v[18:19], v[18:19], v[40:41]
	v_div_fixup_f32 v28, v35, v28, 1.0
	v_pk_mul_f32 v[16:17], v[28:29], v[16:17] op_sel_hi:[0,1]
	v_pk_mul_f32 v[18:19], v[28:29], v[18:19] op_sel_hi:[0,1]
	s_waitcnt vmcnt(0)
	ds_write_b128 v185, v[36:39] offset:9216
	ds_read_b64 v[36:37], v34 offset:9216
	ds_read_b64 v[38:39], v34 offset:9248
	ds_read_b64 v[32:33], v34 offset:9280
	ds_read_b64 v[24:25], v34 offset:9312
	s_waitcnt lgkmcnt(3)
	v_lshlrev_b32_e32 v40, 16, v36
	v_mul_f32_e32 v35, 0xbfb8aa3b, v40
	v_exp_f32_e32 v35, v35
	v_and_b32_e32 v41, 0xffff0000, v36
	v_lshlrev_b32_e32 v36, 16, v37
	v_and_b32_e32 v37, 0xffff0000, v37
	v_add_f32_e32 v35, 1.0, v35
	v_rcp_f32_e32 v42, v35
	v_mul_f32_e32 v35, 0xbfb8aa3b, v41
	v_exp_f32_e32 v35, v35
	s_nop 0
	v_add_f32_e32 v35, 1.0, v35
	v_rcp_f32_e32 v43, v35
	s_nop 0
	v_pk_mul_f32 v[40:41], v[42:43], v[40:41]
	s_nop 0
	v_pk_mul_f32 v[16:17], v[16:17], v[40:41]
	s_nop 0
	v_cvt_pk_bf16_f32 v16, v16, v17
	v_mul_f32_e32 v17, 0xbfb8aa3b, v36
	v_exp_f32_e32 v17, v17
	s_nop 0
	v_add_f32_e32 v17, 1.0, v17
	v_rcp_f32_e32 v40, v17
	v_mul_f32_e32 v17, 0xbfb8aa3b, v37
	v_exp_f32_e32 v17, v17
	s_nop 0
	v_add_f32_e32 v17, 1.0, v17
	v_rcp_f32_e32 v41, v17
	s_nop 0
	v_pk_mul_f32 v[36:37], v[40:41], v[36:37]
	s_nop 0
	v_pk_mul_f32 v[18:19], v[18:19], v[36:37]
	s_nop 0
	v_cvt_pk_bf16_f32 v17, v18, v19
	v_lshlrev_b32_e32 v18, 16, v44
	v_and_b32_e32 v19, 0xffff0000, v44
	v_pk_add_f32 v[12:13], v[12:13], v[18:19]
	v_lshlrev_b32_e32 v18, 16, v45
	v_and_b32_e32 v19, 0xffff0000, v45
	v_pk_add_f32 v[14:15], v[14:15], v[18:19]
	s_waitcnt lgkmcnt(2)
; #define LAS __attribute__((address_space(3)))
; DI unsigned pk2(float lo, float hi) { f32x2_t v = {lo, hi}; bf16x2_t b = __builtin_convertvector(v, bf16x2_t); return __builtin_bit_cast(unsigned, b); }
; DI float silu_f(float x) { return x * __builtin_amdgcn_rcpf(1.f + __expf(-x)); }
; #define LAUNDER() int tp = TID0(); const int tid = tp, lane = tp & 63, wave = __builtin_amdgcn_readfirstlane(tp >> 6); (void)tid; (void)lane; (void)wave
; DI void mixerA2_unit(int u, const bf16* PROJ, bf16* YC, const float* LPA, const float* kmax_l, LAS char* vt, int wave, int lane) {
;     ...
;     for (int c = 0; c < 4; ++c) {
;         f32x4 ov = o[c]; ov[0] += bflo(pv[c].x); ov[1] += bfhi(pv[c].x); ov[2] += bflo(pv[c].y); ov[3] += bfhi(pv[c].y); ov = ov * inv;
;         u32x2 w; w.x = pk2(ov[0] * silu_f(bflo(gv[c].x)), ov[1] * silu_f(bfhi(gv[c].x))); w.y = pk2(ov[2] * silu_f(bflo(gv[c].y)), ov[3] * silu_f(bfhi(gv[c].y)));
;         *(LAS u32x2*)(sc + r * VT_PITCH + (16 * c + 4 * g) * 2) = w; }
;     rows16_store(sc, ybase, 1024, tok0, 16, lane);
; }
; __global__ void __launch_bounds__(512) fwd_kernel(Args a) {
;     ...
;         if (IN(pb + 3) && EN_A) { LAUNDER(); LAS char* vt = (LAS char*)lds + wave * 16384;
;             for (int u = blockIdx.x; u < 512; u += G) { mixerA2_unit(u, PROJ, YC, LPA, KMAX + l * 1024, vt, wave, lane); } }
	v_lshlrev_b32_e32 v18, 16, v38
	v_mul_f32_e32 v35, 0xbfb8aa3b, v18
	v_exp_f32_e32 v35, v35
	v_and_b32_e32 v19, 0xffff0000, v38
	v_pk_mul_f32 v[12:13], v[28:29], v[12:13] op_sel_hi:[0,1]
	v_pk_mul_f32 v[14:15], v[28:29], v[14:15] op_sel_hi:[0,1]
	v_add_f32_e32 v35, 1.0, v35
	v_rcp_f32_e32 v36, v35
	v_mul_f32_e32 v35, 0xbfb8aa3b, v19
	v_exp_f32_e32 v35, v35
	s_nop 0
	v_add_f32_e32 v35, 1.0, v35
	v_rcp_f32_e32 v37, v35
	s_nop 0
	v_pk_mul_f32 v[18:19], v[36:37], v[18:19]
	s_nop 0
	v_pk_mul_f32 v[12:13], v[12:13], v[18:19]
	v_lshlrev_b32_e32 v18, 16, v39
	v_cvt_pk_bf16_f32 v12, v12, v13
	v_mul_f32_e32 v13, 0xbfb8aa3b, v18
	v_exp_f32_e32 v13, v13
	v_and_b32_e32 v19, 0xffff0000, v39
	v_add_f32_e32 v13, 1.0, v13
	v_rcp_f32_e32 v36, v13
	v_mul_f32_e32 v13, 0xbfb8aa3b, v19
	v_exp_f32_e32 v13, v13
	s_nop 0
	v_add_f32_e32 v13, 1.0, v13
	v_rcp_f32_e32 v37, v13
	s_nop 0
	v_pk_mul_f32 v[18:19], v[36:37], v[18:19]
	s_nop 0
	v_pk_mul_f32 v[14:15], v[14:15], v[18:19]
	s_nop 0
	v_cvt_pk_bf16_f32 v13, v14, v15
	v_add_u32_e32 v14, 0x2000, v34
	ds_write2_b64 v14, v[16:17], v[12:13] offset0:128 offset1:132
	v_lshlrev_b32_e32 v12, 16, v30
	v_and_b32_e32 v13, 0xffff0000, v30
	v_pk_add_f32 v[8:9], v[8:9], v[12:13]
	v_lshlrev_b32_e32 v12, 16, v31
	v_and_b32_e32 v13, 0xffff0000, v31
	v_pk_add_f32 v[10:11], v[10:11], v[12:13]
	s_waitcnt lgkmcnt(2)
	v_lshlrev_b32_e32 v12, 16, v32
	v_mul_f32_e32 v15, 0xbfb8aa3b, v12
	v_exp_f32_e32 v15, v15
	v_and_b32_e32 v13, 0xffff0000, v32
	v_pk_mul_f32 v[8:9], v[28:29], v[8:9] op_sel_hi:[0,1]
	v_pk_mul_f32 v[10:11], v[28:29], v[10:11] op_sel_hi:[0,1]
	v_add_f32_e32 v15, 1.0, v15
	v_rcp_f32_e32 v16, v15
	v_mul_f32_e32 v15, 0xbfb8aa3b, v13
	v_exp_f32_e32 v15, v15
	s_nop 0
	v_add_f32_e32 v15, 1.0, v15
	v_rcp_f32_e32 v17, v15
	s_nop 0
	v_pk_mul_f32 v[12:13], v[16:17], v[12:13]
	s_nop 0
	v_pk_mul_f32 v[8:9], v[8:9], v[12:13]
	v_lshlrev_b32_e32 v12, 16, v33
	v_cvt_pk_bf16_f32 v8, v8, v9
	v_mul_f32_e32 v9, 0xbfb8aa3b, v12
	v_exp_f32_e32 v9, v9
	v_and_b32_e32 v13, 0xffff0000, v33
	v_add_f32_e32 v9, 1.0, v9
	v_rcp_f32_e32 v16, v9
	v_mul_f32_e32 v9, 0xbfb8aa3b, v13
	v_exp_f32_e32 v9, v9
	s_nop 0
	v_add_f32_e32 v9, 1.0, v9
	v_rcp_f32_e32 v17, v9
	s_nop 0
	v_pk_mul_f32 v[12:13], v[16:17], v[12:13]
	s_nop 0
	v_pk_mul_f32 v[10:11], v[10:11], v[12:13]
	s_nop 0
	v_cvt_pk_bf16_f32 v9, v10, v11
	v_lshlrev_b32_e32 v10, 16, v26
	v_and_b32_e32 v11, 0xffff0000, v26
	v_pk_add_f32 v[10:11], v[4:5], v[10:11]
	v_lshlrev_b32_e32 v4, 16, v27
	v_and_b32_e32 v5, 0xffff0000, v27
	v_pk_add_f32 v[4:5], v[6:7], v[4:5]
	v_pk_mul_f32 v[6:7], v[28:29], v[10:11] op_sel_hi:[0,1]
	s_waitcnt lgkmcnt(1)
	v_lshlrev_b32_e32 v10, 16, v24
	v_and_b32_e32 v11, 0xffff0000, v24
	v_mul_f32_e32 v12, 0xbfb8aa3b, v10
	v_mul_f32_e32 v13, 0xbfb8aa3b, v11
	v_exp_f32_e32 v12, v12
	v_exp_f32_e32 v13, v13
	v_pk_mul_f32 v[4:5], v[28:29], v[4:5] op_sel_hi:[0,1]
	v_add_f32_e32 v12, 1.0, v12
	v_add_f32_e32 v13, 1.0, v13
	v_rcp_f32_e32 v12, v12
	v_rcp_f32_e32 v13, v13
	s_nop 0
	v_pk_mul_f32 v[10:11], v[12:13], v[10:11]
	s_nop 0
	v_pk_mul_f32 v[6:7], v[6:7], v[10:11]
	v_lshlrev_b32_e32 v10, 16, v25
	v_cvt_pk_bf16_f32 v6, v6, v7
	v_mul_f32_e32 v7, 0xbfb8aa3b, v10
	v_exp_f32_e32 v7, v7
	v_and_b32_e32 v11, 0xffff0000, v25
	v_add_f32_e32 v7, 1.0, v7
	v_rcp_f32_e32 v12, v7
	v_mul_f32_e32 v7, 0xbfb8aa3b, v11
	v_exp_f32_e32 v7, v7
	s_nop 0
	v_add_f32_e32 v7, 1.0, v7
	v_rcp_f32_e32 v13, v7
	s_nop 0
	v_pk_mul_f32 v[10:11], v[12:13], v[10:11]
	s_nop 0
	v_pk_mul_f32 v[4:5], v[4:5], v[10:11]
	s_nop 0
	v_cvt_pk_bf16_f32 v7, v4, v5
	ds_write2_b64 v14, v[8:9], v[6:7] offset0:136 offset1:140
	ds_read_b128 v[4:7], v29 offset:9216
	s_waitcnt lgkmcnt(0)
	global_store_dwordx4 v[20:21], v[4:7], off
	ds_read_b128 v[4:7], v185 offset:9216
	s_waitcnt lgkmcnt(0)
	global_store_dwordx4 v[22:23], v[4:7], off
	s_cbranch_scc1 .LBB0_421
	v_readlane_b32 s94, v255, 33
	v_readlane_b32 s90, v255, 23
	v_readlane_b32 s58, v253, 24
	v_readlane_b32 s26, v255, 35
	v_readlane_b32 s95, v255, 34
	s_mov_b64 s[96:97], s[56:57]
	v_readlane_b32 s56, v255, 21
	v_readlane_b32 s91, v255, 24
	v_readlane_b32 s59, v253, 25
	v_readlane_b32 s27, v255, 36
	v_readlane_b32 s57, v255, 22
